# X2: the two prompt pairs of a workgroup share (batch, head) so K/V^T are staged once; X2 sample block on f32 MFMA
# speedup vs baseline: 1.0137x; 1.0137x over previous
; __device__ __forceinline__ float bf_lo(unsigned w) { return __uint_as_float(w << 16); }
; __device__ __forceinline__ float bf_hi(unsigned w) { return __uint_as_float(w & 0xffff0000u); }
; __device__ __forceinline__ void gate_sample_item(const bf16_t* z, bf16_t* mix, float* cvs  , const float* w_s, const float* b_s,
;                                                  const float* lnv_g, const float* lnv_b, int it, int lane) {
;     ...
;     const int c = cq * 128 + 2 * lane;
;     float vn0[8], vn1[8];
; #pragma unroll
;     for (int j = 0; j < 8; ++j) {
;         const bf16_t* vp = z + (tok0 + j) * EIN + 3328 + lane * 16;
;         const u32x4 a = *(const u32x4*)vp, cc = *(const u32x4*)(vp + 8);
;         float v[16] = {bf_lo(a.x), bf_hi(a.x), bf_lo(a.y), bf_hi(a.y), bf_lo(a.z), bf_hi(a.z), bf_lo(a.w), bf_hi(a.w),
;                        bf_lo(cc.x), bf_hi(cc.x), bf_lo(cc.y), bf_hi(cc.y), bf_lo(cc.z), bf_hi(cc.z), bf_lo(cc.w), bf_hi(cc.w)};
;         float s = 0.f;
; #pragma unroll
;         for (int e = 0; e < 16; ++e) s += v[e];
;         const float mean = wave_sum(s) * (1.0f / 1024.0f);
;         float q = 0.f;
; #pragma unroll
;         for (int e = 0; e < 16; ++e) { const float d = v[e] - mean; q += d * d; }
;         const float rstd = rsqrtf(wave_sum(q) * (1.0f / 1024.0f) + EPSN);
;         const unsigned xw = *(const unsigned*)(z + (tok0 + j) * EIN + 3328 + c);
;         vn0[j] = (bf_lo(xw) - mean) * rstd * lnv_g[c] + lnv_b[c];
;         vn1[j] = (bf_hi(xw) - mean) * rstd * lnv_g[c + 1] + lnv_b[c + 1];
;         *(f32x2*)(cvs + ((size_t)b * 8 + j) * 1024 + c) = (f32x2){vn0[j], vn1[j]};
;     }
.LBB0_1091:
	v_readlane_b32 s4, v254, 52
	v_readlane_b32 s5, v254, 53
	s_lshl_b64 s[4:5], s[4:5], 20
	v_readlane_b32 s6, v255, 1
	v_readlane_b32 s7, v255, 2
	s_add_u32 s4, s6, s4
	s_addc_u32 s5, s7, s5
	s_add_u32 s12, s4, 0x16280000
	v_readlane_b32 s4, v255, 0
	s_addc_u32 s13, s5, 0
	s_and_b32 s4, s4, 0x1c0
	v_lshlrev_b32_e32 v0, 4, v82
	s_cmpk_eq_i32 s4, 0x80
	s_cselect_b64 s[4:5], -1, 0
	v_lshlrev_b32_e32 v27, 1, v0
	s_cmpk_lg_i32 s88, 0x100
	s_cbranch_scc1 .LBB0_1093
	s_lshr_b32 s16, s54, 3
	s_and_b32 s17, s54, 7
	s_and_b32 s18, s16, 7
	s_lshr_b32 s19, s16, 3
	s_lshr_b32 s20, s18, 1
	v_readlane_b32 s22, v254, 42
	v_readlane_b32 s23, v254, 43
	v_readlane_b32 s24, v255, 7
	v_readlane_b32 s25, v255, 8
	s_lshl_b32 s21, s19, 3
	s_add_i32 s21, s21, s17
	s_mul_i32 s26, s21, 0x2a00
	s_add_u32 s26, s26, 0x5400000
	s_add_u32 s28, s22, 0x13e08000
	s_addc_u32 s29, s23, 0
	s_add_u32 s28, s28, s26
	s_addc_u32 s29, s29, 0
	s_add_u32 s30, s28, 0x1a00
	s_addc_u32 s31, s29, 0
	s_lshl_b32 s27, s18, 8
	s_add_u32 s34, s30, s27
	s_addc_u32 s35, s31, 0
	v_lshlrev_b32_e32 v0, 5, v215
	v_lshlrev_b32_e32 v28, 2, v215
	v_lshlrev_b32_e32 v29, 3, v215
	global_load_dwordx4 v[2:5], v0, s[30:31]
	global_load_dwordx4 v[6:9], v0, s[30:31] offset:16
	global_load_dword v10, v28, s[34:35]
	s_lshl_b32 s27, s18, 9
	s_add_u32 s36, s76, s27
	s_addc_u32 s37, s77, 0
	global_load_dwordx2 v[12:13], v29, s[36:37]
	s_add_u32 s38, s78, s27
	s_addc_u32 s39, s79, 0
	global_load_dwordx2 v[14:15], v29, s[38:39]
	global_load_dword v11, v28, s[34:35] offset:-2048
	global_load_dword v16, v28, s[34:35] offset:2048
	s_lshl_b32 s27, s20, 7
	s_add_i32 s27, s27, s17
	s_lshl_b32 s36, s27, 2
	s_add_u32 s24, s24, s36
	s_addc_u32 s25, s25, 0
	global_load_dword v17, v1, s[24:25]
	s_lshl_b32 s36, s27, 9
	s_add_u32 s36, s90, s36
	s_addc_u32 s37, s91, 0
	global_load_dwordx4 v[18:21], v1, s[36:37]
	global_load_dwordx4 v[22:25], v1, s[36:37] offset:16
	s_waitcnt vmcnt(8)
	v_lshlrev_b32_e32 v30, 16, v2
	v_and_b32_e32 v31, 0xffff0000, v2
	v_lshlrev_b32_e32 v32, 16, v3
	v_and_b32_e32 v33, 0xffff0000, v3
	v_lshlrev_b32_e32 v34, 16, v4
	v_and_b32_e32 v35, 0xffff0000, v4
	v_lshlrev_b32_e32 v36, 16, v5
	v_and_b32_e32 v37, 0xffff0000, v5
	v_lshlrev_b32_e32 v38, 16, v6
	v_and_b32_e32 v39, 0xffff0000, v6
	v_lshlrev_b32_e32 v40, 16, v7
	v_and_b32_e32 v41, 0xffff0000, v7
	v_lshlrev_b32_e32 v42, 16, v8
	v_and_b32_e32 v43, 0xffff0000, v8
	v_lshlrev_b32_e32 v44, 16, v9
	v_and_b32_e32 v45, 0xffff0000, v9
	v_add_f32_e32 v46, 0, v30
	v_add_f32_e32 v46, v46, v31
	v_add_f32_e32 v46, v46, v32
	v_add_f32_e32 v46, v46, v33
	v_add_f32_e32 v46, v46, v34
	v_add_f32_e32 v46, v46, v35
	v_add_f32_e32 v46, v46, v36
	v_add_f32_e32 v46, v46, v37
	v_add_f32_e32 v46, v46, v38
	v_add_f32_e32 v46, v46, v39
	v_add_f32_e32 v46, v46, v40
	v_add_f32_e32 v46, v46, v41
	v_add_f32_e32 v46, v46, v42
	v_add_f32_e32 v46, v46, v43
	v_add_f32_e32 v46, v46, v44
	v_add_f32_e32 v46, v46, v45
	s_waitcnt lgkmcnt(0)
	s_nop 1
	v_add_f32_dpp v46, v46, v46 quad_perm:[1,0,3,2] row_mask:0xf bank_mask:0xf
	s_nop 1
	v_add_f32_dpp v46, v46, v46 quad_perm:[2,3,0,1] row_mask:0xf bank_mask:0xf
	s_nop 1
	v_add_f32_dpp v46, v46, v46 row_half_mirror row_mask:0xf bank_mask:0xf
	s_nop 1
	v_add_f32_dpp v46, v46, v46 row_mirror row_mask:0xf bank_mask:0xf
	s_nop 1
	v_add_f32_dpp v46, v46, v46 row_bcast:15 row_mask:0xa bank_mask:0xf
	s_nop 1
	v_add_f32_dpp v46, v46, v46 row_bcast:31 row_mask:0xc bank_mask:0xf
	s_nop 1
	v_readlane_b32 s39, v46, 63
	s_nop 1
	v_mov_b32_e32 v46, s39
	v_fmac_f32_e32 v30, 0xba800000, v46
	v_fmac_f32_e32 v31, 0xba800000, v46
	v_fmac_f32_e32 v32, 0xba800000, v46
	v_fmac_f32_e32 v33, 0xba800000, v46
	v_fmac_f32_e32 v34, 0xba800000, v46
	v_fmac_f32_e32 v35, 0xba800000, v46
	v_fmac_f32_e32 v36, 0xba800000, v46
	v_fmac_f32_e32 v37, 0xba800000, v46
	v_fmac_f32_e32 v38, 0xba800000, v46
	v_fmac_f32_e32 v39, 0xba800000, v46
	v_fmac_f32_e32 v40, 0xba800000, v46
	v_fmac_f32_e32 v41, 0xba800000, v46
	v_fmac_f32_e32 v42, 0xba800000, v46
	v_fmac_f32_e32 v43, 0xba800000, v46
	v_fmac_f32_e32 v44, 0xba800000, v46
	v_fmac_f32_e32 v45, 0xba800000, v46
	v_mul_f32_e32 v47, v30, v30
	v_fmac_f32_e32 v47, v31, v31
	v_fmac_f32_e32 v47, v32, v32
	v_fmac_f32_e32 v47, v33, v33
	v_fmac_f32_e32 v47, v34, v34
	v_fmac_f32_e32 v47, v35, v35
	v_fmac_f32_e32 v47, v36, v36
	v_fmac_f32_e32 v47, v37, v37
	v_fmac_f32_e32 v47, v38, v38
	v_fmac_f32_e32 v47, v39, v39
	v_fmac_f32_e32 v47, v40, v40
	v_fmac_f32_e32 v47, v41, v41
	v_fmac_f32_e32 v47, v42, v42
	v_fmac_f32_e32 v47, v43, v43
	v_fmac_f32_e32 v47, v44, v44
	v_fmac_f32_e32 v47, v45, v45
	s_waitcnt lgkmcnt(0)
	s_nop 1
	v_add_f32_dpp v47, v47, v47 quad_perm:[1,0,3,2] row_mask:0xf bank_mask:0xf
	s_nop 1
	v_add_f32_dpp v47, v47, v47 quad_perm:[2,3,0,1] row_mask:0xf bank_mask:0xf
	s_nop 1
	v_add_f32_dpp v47, v47, v47 row_half_mirror row_mask:0xf bank_mask:0xf
	s_nop 1
	v_add_f32_dpp v47, v47, v47 row_mirror row_mask:0xf bank_mask:0xf
	s_nop 1
	v_add_f32_dpp v47, v47, v47 row_bcast:15 row_mask:0xa bank_mask:0xf
	s_nop 1
	v_add_f32_dpp v47, v47, v47 row_bcast:31 row_mask:0xc bank_mask:0xf
	s_nop 1
	v_readlane_b32 s39, v47, 63
	s_nop 1
	v_mov_b32_e32 v47, s39
	v_fmamk_f32 v47, v47, 0x3a800000, v138
	v_rsq_f32_e32 v47, v47
	v_mul_f32_e32 v48, 0x3a800000, v46
	s_waitcnt vmcnt(5)
	v_lshlrev_b32_e32 v30, 16, v10
	v_and_b32_e32 v31, 0xffff0000, v10
	v_sub_f32_e32 v30, v30, v48
	v_sub_f32_e32 v31, v31, v48
	v_mul_f32_e32 v30, v30, v47
	v_mul_f32_e32 v31, v31, v47
	v_pk_fma_f32 v[32:33], v[12:13], v[30:31], v[14:15]
	s_lshl_b32 s36, s21, 12
	s_lshl_b32 s27, s18, 9
	s_add_i32 s36, s36, s27
	s_add_u32 s36, s12, s36
	s_addc_u32 s37, s13, 0
	s_lshl_b32 s27, s17, 9
	v_add_u32_e32 v34, s27, v29
	v_add_u32_e32 v34, 0xa000, v34
	global_store_dwordx2 v29, v[32:33], s[36:37]
	ds_write_b64 v34, v[32:33]
	s_waitcnt lgkmcnt(0)
	s_barrier
; __device__ __forceinline__ float bf_lo(unsigned w) { return __uint_as_float(w << 16); }
; __device__ __forceinline__ float bf_hi(unsigned w) { return __uint_as_float(w & 0xffff0000u); }
; __device__ __forceinline__ unsigned pk2(float lo, float hi) { return pg8::cvt_pk_bf16(lo, hi); }
; __device__ __forceinline__ void gate_sample_item(const bf16_t* z, bf16_t* mix, float* cvs  , const float* w_s, const float* b_s,
;                                                  const float* lnv_g, const float* lnv_b, int it, int lane) {
;     ...
;     for (int t = 0; t < 8; ++t) {
;         float m0 = b_s[gr * 128 + t], m1 = m0;
; #pragma unroll
;         for (int j = 0; j < 8; ++j)
;             if (j <= t) { const float w = w_s[((size_t)gr * 128 + t) * 128 + j]; m0 += w * vn0[j]; m1 += w * vn1[j]; }
;         const unsigned uw = *(const unsigned*)(z + (tok0 + t) * EIN + 2304 + c), gw = *(const unsigned*)(z + (tok0 + t) * EIN + 4352 + c);
;         *(unsigned*)(mix + (tok0 + t) * 2048 + 1024 + c) = pk2(bf_lo(gw) * bf_lo(uw) * m0, bf_hi(gw) * bf_hi(uw) * m1);
;     }
	v_add_u32_e32 v49, 0xa000, v29
	ds_read_b64 v[30:31], v49 offset:0
	ds_read_b64 v[32:33], v49 offset:512
	ds_read_b64 v[34:35], v49 offset:1024
	ds_read_b64 v[36:37], v49 offset:1536
	ds_read_b64 v[38:39], v49 offset:2048
	ds_read_b64 v[40:41], v49 offset:2560
	ds_read_b64 v[42:43], v49 offset:3072
	ds_read_b64 v[44:45], v49 offset:3584
	s_waitcnt vmcnt(1)
	v_mov_b32_e32 v46, v17
	v_mov_b32_e32 v47, v17
	v_lshlrev_b32_e32 v2, 16, v11
	v_and_b32_e32 v3, 0xffff0000, v11
	v_lshlrev_b32_e32 v4, 16, v16
	v_and_b32_e32 v5, 0xffff0000, v16
	v_pk_mul_f32 v[2:3], v[4:5], v[2:3]
	s_waitcnt lgkmcnt(0)
	v_fmac_f32_e32 v46, v18, v30
	v_fmac_f32_e32 v47, v18, v31
	s_cmp_lt_u32 s17, 1
	s_cbranch_scc1 .Lsg_done
	v_fmac_f32_e32 v46, v19, v32
	v_fmac_f32_e32 v47, v19, v33
	s_cmp_lt_u32 s17, 2
	s_cbranch_scc1 .Lsg_done
	v_fmac_f32_e32 v46, v20, v34
	v_fmac_f32_e32 v47, v20, v35
	s_cmp_lt_u32 s17, 3
	s_cbranch_scc1 .Lsg_done
	v_fmac_f32_e32 v46, v21, v36
	v_fmac_f32_e32 v47, v21, v37
	s_cmp_lt_u32 s17, 4
	s_cbranch_scc1 .Lsg_done
	v_fmac_f32_e32 v46, v22, v38
	v_fmac_f32_e32 v47, v22, v39
	s_cmp_lt_u32 s17, 5
	s_cbranch_scc1 .Lsg_done
	v_fmac_f32_e32 v46, v23, v40
	v_fmac_f32_e32 v47, v23, v41
	s_cmp_lt_u32 s17, 6
	s_cbranch_scc1 .Lsg_done
	v_fmac_f32_e32 v46, v24, v42
	v_fmac_f32_e32 v47, v24, v43
	s_cmp_lt_u32 s17, 7
	s_cbranch_scc1 .Lsg_done
	v_fmac_f32_e32 v46, v25, v44
	v_fmac_f32_e32 v47, v25, v45

; #define LAS __attribute__((address_space(3)))
; __device__ __forceinline__ float bf_lo(unsigned w) { return __uint_as_float(w << 16); }
; __device__ __forceinline__ float bf_hi(unsigned w) { return __uint_as_float(w & 0xffff0000u); }
; __device__ __forceinline__ void xattn_sample_block(LAS unsigned char* lds, const bf16_t* xq, const bf16_t* xq1, const float* mk, const float* mv, bf16_t* xo, int it, int tid) {
;     const int h = it & 3, b = it >> 2, wave = tid >> 6, lane = tid & 63;
;     LAS float* qs = (LAS float*)lds;
;     LAS float* pT = qs + 1024;
;     LAS float* ml = pT + 2048;
;     LAS float* po = ml + 64;
;     const size_t tok0 = (size_t)T_P + b * 8;
;     if (wave < 4) {
; #pragma unroll
;         for (int t2 = 0; t2 < 2; ++t2) {
;             const int t = wave * 2 + t2;
;             const unsigned qw = *(const unsigned*)(xq + (tok0 + t) * 512 + h * 128 + 2 * lane), qw1 = *(const unsigned*)(xq1 + (tok0 + t) * 512 + h * 128 + 2 * lane);
;             *(LAS f32x2*)(qs + t * 128 + 2 * lane) = (f32x2){(bf_lo(qw) + bf_lo(qw1)) * 0.08838834764831845f, (bf_hi(qw) + bf_hi(qw1)) * 0.08838834764831845f};
;         }
;     }
;     __syncthreads();
;     if (wave < 4) {
;         const int key = lane + 64 * wave;
;         float s[8];
; #pragma unroll
;         for (int t = 0; t < 8; ++t) s[t] = 0.f;
;         const f32x4* kp = (const f32x4*)(mk + (((size_t)b * 256 + key) * 4 + h) * 128);
; #pragma unroll 8
;         for (int d4 = 0; d4 < 32; ++d4) {
;             const f32x4 k4 = kp[d4];
; #pragma unroll
;             for (int t = 0; t < 8; ++t) { const f32x4 q4 = *(const LAS f32x4*)(qs + t * 128 + 4 * d4); s[t] += (k4[0] * q4[0] + k4[1] * q4[1]) + (k4[2] * q4[2] + k4[3] * q4[3]); }
;         }
.LBB0_1371:
	v_readlane_b32 s6, v254, 0
	s_cmp_ge_i32 s52, s6
	s_cselect_b64 s[8:9], -1, 0
	s_and_b64 s[4:5], s[4:5], s[8:9]
	s_andn2_b64 vcc, exec, s[4:5]
	v_readlane_b32 s7, v254, 1
	s_cbranch_vccnz .LBB0_1405
	v_mov_b32_e32 v18, v139
	s_mov_b32 s26, s90
	s_mov_b32 s4, 5
	s_ashr_i32 s5, s4, 31
	s_lshl_b64 s[4:5], s[4:5], 3
	s_add_u32 s4, s96, s4
	s_addc_u32 s5, s97, s5
	s_load_dwordx2 s[22:23], s[4:5], 0x0
	s_mov_b32 s4, 6
	s_waitcnt lgkmcnt(0)
	s_ashr_i32 s5, s4, 31
	s_lshl_b64 s[4:5], s[4:5], 3
	s_add_u32 s4, s96, s4
	s_addc_u32 s5, s97, s5
	s_load_dwordx2 s[20:21], s[4:5], 0x0
	v_readlane_b32 s4, v254, 40
	v_readlane_b32 s5, v254, 41
	v_readlane_b32 s6, v254, 42
	v_readlane_b32 s7, v254, 43
	s_mov_b64 s[4:5], s[6:7]
	s_waitcnt lgkmcnt(0)
	s_add_u32 s10, s4, 0x29228000
	s_addc_u32 s11, s5, 0
	s_mov_b64 s[4:5], s[6:7]
	s_add_u32 s12, s4, 0x13e08000
	s_addc_u32 s13, s5, 0
	s_mov_b64 s[4:5], s[6:7]
	s_add_u32 s14, s4, 0x29a68000
	s_addc_u32 s15, s5, 0
	v_and_b32_e32 v44, 63, v18
	v_readfirstlane_b32 s27, v18
	s_mov_b64 s[18:19], s[6:7]
	s_mov_b64 s[16:17], s[6:7]
	s_mov_b64 s[4:5], s[6:7]
	s_cmp_ge_i32 s26, s82
	s_cbranch_scc0 .LBB0_1402
	s_sub_i32 s28, s26, s82
	s_cmpk_gt_i32 s28, 0x7f
	s_cbranch_scc1 .LBB0_1402
	v_readlane_b32 s24, v254, 36
	v_readlane_b32 s25, v254, 37
	v_and_b32_e32 v50, 15, v215
	v_lshrrev_b32_e32 v51, 4, v215
	s_lshr_b32 s29, s27, 6
	s_add_u32 s22, s22, s24
	s_addc_u32 s23, s23, s25
	s_add_u32 s20, s20, s24
	s_addc_u32 s21, s21, s25
	s_lshl_b32 s30, s29, 16
	v_lshlrev_b32_e32 v52, 11, v50
	v_lshl_add_u32 v52, v51, 4, v52
	v_add_u32_e32 v52, s30, v52
	v_lshlrev_b32_e32 v53, 13, v51
	v_lshl_add_u32 v53, v50, 4, v53
	v_add_u32_e32 v53, s30, v53
	v_and_b32_e32 v54, 7, v50
	v_lshlrev_b32_e32 v54, 9, v54
	v_lshl_add_u32 v54, v51, 4, v54
	v_lshlrev_b32_e32 v55, 2, v139
	v_xor_b32_e32 v56, 16, v215
	v_lshlrev_b32_e32 v56, 2, v56
	v_xor_b32_e32 v57, 32, v215
	v_lshlrev_b32_e32 v57, 2, v57
.Lxs_item:
	s_and_b32 s31, s28, 3
	s_lshr_b32 s4, s28, 2
	s_lshl_b32 s5, s4, 19
	s_lshl_b32 s6, s31, 9
	s_add_i32 s5, s5, s6
	s_add_u32 s16, s22, s5
	s_addc_u32 s17, s23, 0
	s_add_u32 s18, s20, s5
	s_addc_u32 s19, s21, 0
	global_load_dwordx4 v[64:67], v52, s[16:17] offset:0
	global_load_dwordx4 v[68:71], v52, s[16:17] offset:64
	global_load_dwordx4 v[72:75], v52, s[16:17] offset:128
	global_load_dwordx4 v[76:79], v52, s[16:17] offset:192
	global_load_dwordx4 v[80:83], v52, s[16:17] offset:256
	global_load_dwordx4 v[84:87], v52, s[16:17] offset:320
	global_load_dwordx4 v[88:91], v52, s[16:17] offset:384
	global_load_dwordx4 v[92:95], v52, s[16:17] offset:448
	s_add_u32 s16, s16, 0x8000
	s_addc_u32 s17, s17, 0
	global_load_dwordx4 v[96:99], v52, s[16:17] offset:0
	global_load_dwordx4 v[100:103], v52, s[16:17] offset:64
	global_load_dwordx4 v[104:107], v52, s[16:17] offset:128
	global_load_dwordx4 v[108:111], v52, s[16:17] offset:192
	global_load_dwordx4 v[112:115], v52, s[16:17] offset:256
	global_load_dwordx4 v[116:119], v52, s[16:17] offset:320
	global_load_dwordx4 v[120:123], v52, s[16:17] offset:384
	global_load_dwordx4 v[124:127], v52, s[16:17] offset:448
	s_lshl_b32 s5, s4, 3
	s_addk_i32 s5, 0x2000
	s_lshl_b32 s5, s5, 10
	s_lshl_b32 s6, s31, 8
	s_add_i32 s5, s5, s6
	s_add_u32 s24, s10, s5
	s_addc_u32 s25, s11, 0
	v_lshrrev_b32_e32 v58, 6, v139
	v_and_b32_e32 v59, 63, v139
	v_lshlrev_b32_e32 v60, 10, v58
	v_lshl_add_u32 v60, v59, 2, v60
	global_load_dword v61, v60, s[24:25]
	s_add_u32 s24, s12, s5
	s_addc_u32 s25, s13, 0
	global_load_dword v62, v60, s[24:25]
	global_load_dwordx4 v[146:149], v53, s[18:19] offset:0
	global_load_dwordx4 v[150:153], v53, s[18:19] offset:256
	s_add_u32 s18, s18, 0x800
	s_addc_u32 s19, s19, 0
	global_load_dwordx4 v[154:157], v53, s[18:19] offset:0
	global_load_dwordx4 v[158:161], v53, s[18:19] offset:256
	s_add_u32 s18, s18, 0x800
	s_addc_u32 s19, s19, 0
	global_load_dwordx4 v[162:165], v53, s[18:19] offset:0
	global_load_dwordx4 v[166:169], v53, s[18:19] offset:256
	s_add_u32 s18, s18, 0x800
	s_addc_u32 s19, s19, 0
	global_load_dwordx4 v[170:173], v53, s[18:19] offset:0
	global_load_dwordx4 v[174:177], v53, s[18:19] offset:256
	s_add_u32 s18, s18, 0x6800
	s_addc_u32 s19, s19, 0
	global_load_dwordx4 v[178:181], v53, s[18:19] offset:0
	global_load_dwordx4 v[182:185], v53, s[18:19] offset:256
	s_add_u32 s18, s18, 0x800
	s_addc_u32 s19, s19, 0
	global_load_dwordx4 v[186:189], v53, s[18:19] offset:0
	global_load_dwordx4 v[190:193], v53, s[18:19] offset:256
	s_add_u32 s18, s18, 0x800
	s_addc_u32 s19, s19, 0
	global_load_dwordx4 v[194:197], v53, s[18:19] offset:0
	global_load_dwordx4 v[198:201], v53, s[18:19] offset:256
	s_add_u32 s18, s18, 0x800
	s_addc_u32 s19, s19, 0
	global_load_dwordx4 v[202:205], v53, s[18:19] offset:0
	global_load_dwordx4 v[206:209], v53, s[18:19] offset:256
	s_waitcnt vmcnt(16)
	v_lshlrev_b32_e32 v46, 16, v61
	v_and_b32_e32 v47, 0xffff0000, v61
	v_lshlrev_b32_e32 v48, 16, v62
	v_and_b32_e32 v49, 0xffff0000, v62
	v_pk_add_f32 v[46:47], v[46:47], v[48:49]
	v_pk_mul_f32 v[46:47], v[46:47], s[86:87] op_sel_hi:[1,0]
	v_lshlrev_b32_e32 v60, 9, v58
	v_lshl_add_u32 v60, v59, 3, v60
	ds_write_b64 v60, v[46:47]
	s_waitcnt lgkmcnt(0)
	s_barrier
; #define LAS __attribute__((address_space(3)))
; __device__ __forceinline__ void xattn_sample_block(LAS unsigned char* lds, const bf16_t* xq, const bf16_t* xq1, const float* mk, const float* mv, bf16_t* xo, int it, int tid) {
;     ...
;     if (wave < 4) {
;         const int key = lane + 64 * wave;
;         float s[8];
; #pragma unroll
;         for (int t = 0; t < 8; ++t) s[t] = 0.f;
;         const f32x4* kp = (const f32x4*)(mk + (((size_t)b * 256 + key) * 4 + h) * 128);
; #pragma unroll 8
;         for (int d4 = 0; d4 < 32; ++d4) {
;             const f32x4 k4 = kp[d4];
; #pragma unroll
;             for (int t = 0; t < 8; ++t) { const f32x4 q4 = *(const LAS f32x4*)(qs + t * 128 + 4 * d4); s[t] += (k4[0] * q4[0] + k4[1] * q4[1]) + (k4[2] * q4[2] + k4[3] * q4[3]); }
;         }
; #pragma unroll
;         for (int t = 0; t < 8; ++t) {
;             const float m = wave_max(s[t]); const float p = __expf(s[t] - m); const float l = wave_sum(p);
;             pT[key * 8 + t] = p;
;             if (lane == 0) { ml[(wave * 8 + t) * 2] = m; ml[(wave * 8 + t) * 2 + 1] = l; }
;         }
;         __builtin_amdgcn_wave_barrier();
;         asm volatile("s_waitcnt lgkmcnt(0)" ::: "memory");
	ds_read_b128 v[2:5], v54 offset:0
	ds_read_b128 v[6:9], v54 offset:64
	ds_read_b128 v[10:13], v54 offset:128
	ds_read_b128 v[14:17], v54 offset:192
	ds_read_b128 v[18:21], v54 offset:256
	ds_read_b128 v[22:25], v54 offset:320
	ds_read_b128 v[26:29], v54 offset:384
	ds_read_b128 v[30:33], v54 offset:448
	s_waitcnt lgkmcnt(0)
	v_mfma_f32_16x16x4_f32 v[36:39], v64, v2, 0
	v_mfma_f32_16x16x4_f32 v[40:43], v96, v2, 0
	v_mfma_f32_16x16x4_f32 v[36:39], v65, v3, v[36:39]
	v_mfma_f32_16x16x4_f32 v[40:43], v97, v3, v[40:43]
	v_mfma_f32_16x16x4_f32 v[36:39], v66, v4, v[36:39]
	v_mfma_f32_16x16x4_f32 v[40:43], v98, v4, v[40:43]
	v_mfma_f32_16x16x4_f32 v[36:39], v67, v5, v[36:39]
	v_mfma_f32_16x16x4_f32 v[40:43], v99, v5, v[40:43]
	v_mfma_f32_16x16x4_f32 v[36:39], v68, v6, v[36:39]
	v_mfma_f32_16x16x4_f32 v[40:43], v100, v6, v[40:43]
	v_mfma_f32_16x16x4_f32 v[36:39], v69, v7, v[36:39]
	v_mfma_f32_16x16x4_f32 v[40:43], v101, v7, v[40:43]
	v_mfma_f32_16x16x4_f32 v[36:39], v70, v8, v[36:39]
	v_mfma_f32_16x16x4_f32 v[40:43], v102, v8, v[40:43]
	v_mfma_f32_16x16x4_f32 v[36:39], v71, v9, v[36:39]
	v_mfma_f32_16x16x4_f32 v[40:43], v103, v9, v[40:43]
	v_mfma_f32_16x16x4_f32 v[36:39], v72, v10, v[36:39]
	v_mfma_f32_16x16x4_f32 v[40:43], v104, v10, v[40:43]
	v_mfma_f32_16x16x4_f32 v[36:39], v73, v11, v[36:39]
	v_mfma_f32_16x16x4_f32 v[40:43], v105, v11, v[40:43]
	v_mfma_f32_16x16x4_f32 v[36:39], v74, v12, v[36:39]
	v_mfma_f32_16x16x4_f32 v[40:43], v106, v12, v[40:43]
	v_mfma_f32_16x16x4_f32 v[36:39], v75, v13, v[36:39]
	v_mfma_f32_16x16x4_f32 v[40:43], v107, v13, v[40:43]
	v_mfma_f32_16x16x4_f32 v[36:39], v76, v14, v[36:39]
	v_mfma_f32_16x16x4_f32 v[40:43], v108, v14, v[40:43]
	v_mfma_f32_16x16x4_f32 v[36:39], v77, v15, v[36:39]
	v_mfma_f32_16x16x4_f32 v[40:43], v109, v15, v[40:43]
	v_mfma_f32_16x16x4_f32 v[36:39], v78, v16, v[36:39]
	v_mfma_f32_16x16x4_f32 v[40:43], v110, v16, v[40:43]
	v_mfma_f32_16x16x4_f32 v[36:39], v79, v17, v[36:39]
	v_mfma_f32_16x16x4_f32 v[40:43], v111, v17, v[40:43]
	v_mfma_f32_16x16x4_f32 v[36:39], v80, v18, v[36:39]
	v_mfma_f32_16x16x4_f32 v[40:43], v112, v18, v[40:43]
	v_mfma_f32_16x16x4_f32 v[36:39], v81, v19, v[36:39]
	v_mfma_f32_16x16x4_f32 v[40:43], v113, v19, v[40:43]
	v_mfma_f32_16x16x4_f32 v[36:39], v82, v20, v[36:39]
	v_mfma_f32_16x16x4_f32 v[40:43], v114, v20, v[40:43]
	v_mfma_f32_16x16x4_f32 v[36:39], v83, v21, v[36:39]
	v_mfma_f32_16x16x4_f32 v[40:43], v115, v21, v[40:43]
	v_mfma_f32_16x16x4_f32 v[36:39], v84, v22, v[36:39]
	v_mfma_f32_16x16x4_f32 v[40:43], v116, v22, v[40:43]
	v_mfma_f32_16x16x4_f32 v[36:39], v85, v23, v[36:39]
	v_mfma_f32_16x16x4_f32 v[40:43], v117, v23, v[40:43]
	v_mfma_f32_16x16x4_f32 v[36:39], v86, v24, v[36:39]
	v_mfma_f32_16x16x4_f32 v[40:43], v118, v24, v[40:43]
	v_mfma_f32_16x16x4_f32 v[36:39], v87, v25, v[36:39]
	v_mfma_f32_16x16x4_f32 v[40:43], v119, v25, v[40:43]
	v_mfma_f32_16x16x4_f32 v[36:39], v88, v26, v[36:39]
	v_mfma_f32_16x16x4_f32 v[40:43], v120, v26, v[40:43]
	v_mfma_f32_16x16x4_f32 v[36:39], v89, v27, v[36:39]
	v_mfma_f32_16x16x4_f32 v[40:43], v121, v27, v[40:43]
	v_mfma_f32_16x16x4_f32 v[36:39], v90, v28, v[36:39]
	v_mfma_f32_16x16x4_f32 v[40:43], v122, v28, v[40:43]
	v_mfma_f32_16x16x4_f32 v[36:39], v91, v29, v[36:39]
	v_mfma_f32_16x16x4_f32 v[40:43], v123, v29, v[40:43]
	v_mfma_f32_16x16x4_f32 v[36:39], v92, v30, v[36:39]
	v_mfma_f32_16x16x4_f32 v[40:43], v124, v30, v[40:43]
	v_mfma_f32_16x16x4_f32 v[36:39], v93, v31, v[36:39]
	v_mfma_f32_16x16x4_f32 v[40:43], v125, v31, v[40:43]
	v_mfma_f32_16x16x4_f32 v[36:39], v94, v32, v[36:39]
	v_mfma_f32_16x16x4_f32 v[40:43], v126, v32, v[40:43]
	v_mfma_f32_16x16x4_f32 v[36:39], v95, v33, v[36:39]
	v_mfma_f32_16x16x4_f32 v[40:43], v127, v33, v[40:43]
	s_nop 7
	s_nop 3
	v_max3_f32 v44, v36, v37, v38
	v_max3_f32 v44, v44, v39, v40
	v_max3_f32 v44, v44, v41, v42
	v_max_f32_e32 v44, v44, v43
	ds_bpermute_b32 v46, v56, v44
	s_waitcnt lgkmcnt(0)
	v_max_f32_e32 v46, v46, v46
	v_max_f32_e32 v44, v44, v46
	ds_bpermute_b32 v46, v57, v44
	s_waitcnt lgkmcnt(0)
	v_max_f32_e32 v46, v46, v46
	v_max_f32_e32 v44, v44, v46
	v_mov_b32_e32 v45, 0
	v_sub_f32_e32 v36, v36, v44
	v_mul_f32_e32 v36, 0x3fb8aa3b, v36
	v_exp_f32_e32 v36, v36
	v_sub_f32_e32 v37, v37, v44
	v_mul_f32_e32 v37, 0x3fb8aa3b, v37
	v_exp_f32_e32 v37, v37
	v_add_f32_e32 v45, v36, v45
	v_sub_f32_e32 v38, v38, v44
	v_mul_f32_e32 v38, 0x3fb8aa3b, v38
	v_exp_f32_e32 v38, v38
	v_add_f32_e32 v45, v37, v45
	v_sub_f32_e32 v39, v39, v44
	v_mul_f32_e32 v39, 0x3fb8aa3b, v39
	v_exp_f32_e32 v39, v39
	v_add_f32_e32 v45, v38, v45
	v_sub_f32_e32 v40, v40, v44
	v_mul_f32_e32 v40, 0x3fb8aa3b, v40
	v_exp_f32_e32 v40, v40
	v_add_f32_e32 v45, v39, v45
	v_sub_f32_e32 v41, v41, v44
	v_mul_f32_e32 v41, 0x3fb8aa3b, v41
	v_exp_f32_e32 v41, v41
	v_add_f32_e32 v45, v40, v45
	v_sub_f32_e32 v42, v42, v44
	v_mul_f32_e32 v42, 0x3fb8aa3b, v42
	v_exp_f32_e32 v42, v42
	v_add_f32_e32 v45, v41, v45
	v_sub_f32_e32 v43, v43, v44
	v_mul_f32_e32 v43, 0x3fb8aa3b, v43
	v_exp_f32_e32 v43, v43
	v_add_f32_e32 v45, v42, v45
	s_nop 0
	v_add_f32_e32 v45, v43, v45
	ds_bpermute_b32 v46, v56, v45
	s_waitcnt lgkmcnt(0)
	v_add_f32_e32 v45, v45, v46
	ds_bpermute_b32 v46, v57, v45
	s_waitcnt lgkmcnt(0)
	v_add_f32_e32 v45, v45, v46
	v_cmp_gt_u32_e32 vcc, 8, v215
	s_lshl_b32 s5, s29, 6
	v_lshl_add_u32 v46, v215, 3, s5
	v_add_u32_e32 v46, 0x1000, v46
	s_and_saveexec_b64 s[6:7], vcc
	ds_write_b64 v46, v[44:45]
	s_or_b64 exec, exec, s[6:7]
	s_waitcnt vmcnt(0)
; #define LAS __attribute__((address_space(3)))
; __device__ __forceinline__ void xattn_sample_block(LAS unsigned char* lds, const bf16_t* xq, const bf16_t* xq1, const float* mk, const float* mv, bf16_t* xo, int it, int tid) {
;     ...
;         f32x2 o[8];
; #pragma unroll
;         for (int t = 0; t < 8; ++t) o[t] = (f32x2){0.f, 0.f};
; #pragma unroll 16
;         for (int kk = 0; kk < 64; ++kk) {
;             const int k2 = 64 * wave + kk;
;             const f32x2 v = *(const f32x2*)(mv + (((size_t)b * 256 + k2) * 4 + h) * 128 + 2 * lane);
;             const f32x4 pa = *(const LAS f32x4*)(pT + k2 * 8), pb = *(const LAS f32x4*)(pT + k2 * 8 + 4);
;             o[0] += pa[0] * v; o[1] += pa[1] * v; o[2] += pa[2] * v; o[3] += pa[3] * v; o[4] += pb[0] * v; o[5] += pb[1] * v; o[6] += pb[2] * v; o[7] += pb[3] * v;
;         }
; #pragma unroll
;         for (int t = 0; t < 8; ++t) *(LAS f32x2*)(po + (wave * 8 + t) * 128 + 2 * lane) = o[t];
;     }
;     __syncthreads();
;     if (wave < 4) {
; #pragma unroll
;         for (int t2 = 0; t2 < 2; ++t2) {
;             const int t = wave * 2 + t2;
;             float m = ml[(0 * 8 + t) * 2];
; #pragma unroll
;             for (int w = 1; w < 4; ++w) m = fmaxf(m, ml[(w * 8 + t) * 2]);
;             float den = 0.f; f32x2 acc = {0.f, 0.f};
; #pragma unroll
;             for (int w = 0; w < 4; ++w) {
;                 const float sc = __expf(ml[(w * 8 + t) * 2] - m);
;                 den += sc * ml[(w * 8 + t) * 2 + 1];
;                 acc += sc * *(const LAS f32x2*)(po + (w * 8 + t) * 128 + 2 * lane);
	v_mfma_f32_16x16x4_f32 v[2:5], v36, v146, 0
	v_mfma_f32_16x16x4_f32 v[6:9], v36, v147, 0
	v_mfma_f32_16x16x4_f32 v[10:13], v36, v148, 0
	v_mfma_f32_16x16x4_f32 v[14:17], v36, v149, 0
	v_mfma_f32_16x16x4_f32 v[18:21], v36, v150, 0
	v_mfma_f32_16x16x4_f32 v[22:25], v36, v151, 0
	v_mfma_f32_16x16x4_f32 v[26:29], v36, v152, 0
	v_mfma_f32_16x16x4_f32 v[30:33], v36, v153, 0
	v_mfma_f32_16x16x4_f32 v[2:5], v37, v154, v[2:5]
	v_mfma_f32_16x16x4_f32 v[6:9], v37, v155, v[6:9]
	v_mfma_f32_16x16x4_f32 v[10:13], v37, v156, v[10:13]
	v_mfma_f32_16x16x4_f32 v[14:17], v37, v157, v[14:17]
	v_mfma_f32_16x16x4_f32 v[18:21], v37, v158, v[18:21]
	v_mfma_f32_16x16x4_f32 v[22:25], v37, v159, v[22:25]
	v_mfma_f32_16x16x4_f32 v[26:29], v37, v160, v[26:29]
	v_mfma_f32_16x16x4_f32 v[30:33], v37, v161, v[30:33]
	v_mfma_f32_16x16x4_f32 v[2:5], v38, v162, v[2:5]
	v_mfma_f32_16x16x4_f32 v[6:9], v38, v163, v[6:9]
	v_mfma_f32_16x16x4_f32 v[10:13], v38, v164, v[10:13]
	v_mfma_f32_16x16x4_f32 v[14:17], v38, v165, v[14:17]
	v_mfma_f32_16x16x4_f32 v[18:21], v38, v166, v[18:21]
	v_mfma_f32_16x16x4_f32 v[22:25], v38, v167, v[22:25]
	v_mfma_f32_16x16x4_f32 v[26:29], v38, v168, v[26:29]
	v_mfma_f32_16x16x4_f32 v[30:33], v38, v169, v[30:33]
	v_mfma_f32_16x16x4_f32 v[2:5], v39, v170, v[2:5]
	v_mfma_f32_16x16x4_f32 v[6:9], v39, v171, v[6:9]
	v_mfma_f32_16x16x4_f32 v[10:13], v39, v172, v[10:13]
	v_mfma_f32_16x16x4_f32 v[14:17], v39, v173, v[14:17]
	v_mfma_f32_16x16x4_f32 v[18:21], v39, v174, v[18:21]
	v_mfma_f32_16x16x4_f32 v[22:25], v39, v175, v[22:25]
	v_mfma_f32_16x16x4_f32 v[26:29], v39, v176, v[26:29]
	v_mfma_f32_16x16x4_f32 v[30:33], v39, v177, v[30:33]
	v_mfma_f32_16x16x4_f32 v[2:5], v40, v178, v[2:5]
	v_mfma_f32_16x16x4_f32 v[6:9], v40, v179, v[6:9]
	v_mfma_f32_16x16x4_f32 v[10:13], v40, v180, v[10:13]
	v_mfma_f32_16x16x4_f32 v[14:17], v40, v181, v[14:17]
	v_mfma_f32_16x16x4_f32 v[18:21], v40, v182, v[18:21]
	v_mfma_f32_16x16x4_f32 v[22:25], v40, v183, v[22:25]
	v_mfma_f32_16x16x4_f32 v[26:29], v40, v184, v[26:29]
	v_mfma_f32_16x16x4_f32 v[30:33], v40, v185, v[30:33]
	v_mfma_f32_16x16x4_f32 v[2:5], v41, v186, v[2:5]
	v_mfma_f32_16x16x4_f32 v[6:9], v41, v187, v[6:9]
	v_mfma_f32_16x16x4_f32 v[10:13], v41, v188, v[10:13]
	v_mfma_f32_16x16x4_f32 v[14:17], v41, v189, v[14:17]
	v_mfma_f32_16x16x4_f32 v[18:21], v41, v190, v[18:21]
	v_mfma_f32_16x16x4_f32 v[22:25], v41, v191, v[22:25]
	v_mfma_f32_16x16x4_f32 v[26:29], v41, v192, v[26:29]
	v_mfma_f32_16x16x4_f32 v[30:33], v41, v193, v[30:33]
	v_mfma_f32_16x16x4_f32 v[2:5], v42, v194, v[2:5]
	v_mfma_f32_16x16x4_f32 v[6:9], v42, v195, v[6:9]
	v_mfma_f32_16x16x4_f32 v[10:13], v42, v196, v[10:13]
	v_mfma_f32_16x16x4_f32 v[14:17], v42, v197, v[14:17]
	v_mfma_f32_16x16x4_f32 v[18:21], v42, v198, v[18:21]
	v_mfma_f32_16x16x4_f32 v[22:25], v42, v199, v[22:25]
	v_mfma_f32_16x16x4_f32 v[26:29], v42, v200, v[26:29]
	v_mfma_f32_16x16x4_f32 v[30:33], v42, v201, v[30:33]
	v_mfma_f32_16x16x4_f32 v[2:5], v43, v202, v[2:5]
	v_mfma_f32_16x16x4_f32 v[6:9], v43, v203, v[6:9]
	v_mfma_f32_16x16x4_f32 v[10:13], v43, v204, v[10:13]
	v_mfma_f32_16x16x4_f32 v[14:17], v43, v205, v[14:17]
	v_mfma_f32_16x16x4_f32 v[18:21], v43, v206, v[18:21]
	v_mfma_f32_16x16x4_f32 v[22:25], v43, v207, v[22:25]
	v_mfma_f32_16x16x4_f32 v[26:29], v43, v208, v[26:29]
	v_mfma_f32_16x16x4_f32 v[30:33], v43, v209, v[30:33]
	s_nop 7
	s_nop 3
	s_lshl_b32 s5, s29, 13
	v_lshl_add_u32 v46, v215, 4, s5
	v_add_u32_e32 v46, 0x2000, v46
	ds_write_b128 v46, v[2:5] offset:0
	ds_write_b128 v46, v[6:9] offset:1024
	ds_write_b128 v46, v[10:13] offset:2048
	ds_write_b128 v46, v[14:17] offset:3072
	ds_write_b128 v46, v[18:21] offset:4096
	ds_write_b128 v46, v[22:25] offset:5120
	ds_write_b128 v46, v[26:29] offset:6144
	ds_write_b128 v46, v[30:33] offset:7168
	s_waitcnt lgkmcnt(0)
	s_barrier
	v_lshlrev_b32_e32 v46, 3, v58
	v_add_u32_e32 v46, 0x1000, v46
	ds_read_b64 v[2:3], v46 offset:0
	ds_read_b64 v[4:5], v46 offset:64
	ds_read_b64 v[6:7], v46 offset:128
	ds_read_b64 v[8:9], v46 offset:192
	ds_read_b64 v[10:11], v46 offset:256
	ds_read_b64 v[12:13], v46 offset:320
	ds_read_b64 v[14:15], v46 offset:384
	ds_read_b64 v[16:17], v46 offset:448
	v_lshlrev_b32_e32 v47, 1, v59
	v_lshrrev_b32_e32 v48, 6, v47
	v_and_b32_e32 v49, 3, v47
	v_lshl_add_u32 v48, v48, 2, v49
	v_lshlrev_b32_e32 v48, 10, v48
	v_bfe_u32 v49, v47, 2, 4
	v_lshrrev_b32_e32 v60, 2, v58
	v_lshl_add_u32 v49, v60, 4, v49
	v_lshl_add_u32 v48, v49, 4, v48
	v_and_b32_e32 v49, 3, v58
	v_lshl_add_u32 v48, v49, 2, v48
	v_add_u32_e32 v48, 0x2000, v48
	ds_read_b32 v18, v48 offset:0
	ds_read_b32 v19, v48 offset:1024
	ds_read_b32 v20, v48 offset:8192
	ds_read_b32 v21, v48 offset:9216
	ds_read_b32 v22, v48 offset:16384
	ds_read_b32 v23, v48 offset:17408
	ds_read_b32 v24, v48 offset:24576
	ds_read_b32 v25, v48 offset:25600
	ds_read_b32 v26, v48 offset:32768
	ds_read_b32 v27, v48 offset:33792
	ds_read_b32 v28, v48 offset:40960
	ds_read_b32 v29, v48 offset:41984
	ds_read_b32 v30, v48 offset:49152
	ds_read_b32 v31, v48 offset:50176
	ds_read_b32 v32, v48 offset:57344
	ds_read_b32 v33, v48 offset:58368
	s_waitcnt lgkmcnt(0)
; #define LAS __attribute__((address_space(3)))
; __device__ __forceinline__ float bf_lo(unsigned w) { return __uint_as_float(w << 16); }
; __device__ __forceinline__ float bf_hi(unsigned w) { return __uint_as_float(w & 0xffff0000u); }
; __device__ __forceinline__ unsigned pk2(float lo, float hi) { return pg8::cvt_pk_bf16(lo, hi); }
; __device__ __forceinline__ void xattn_prompt_item(const bf16_t* xq, const bf16_t* xq1, const bf16_t* memkv, const bf16_t* memvt, bf16_t* xo, int l, int it, int lane) {
;     const int h = it & 3, qt = it >> 2, b = qt >> 8;
;     const int l15 = lane & 15, g = lane >> 4;
;     const size_t tok = (size_t)qt * 16 + l15;
;     bf16x8 qf[4];
; #pragma unroll
;     for (int ks = 0; ks < 4; ++ks) {
;         const u32x4 a = *(const u32x4*)(xq + tok * 512 + h * 128 + 32 * ks + 8 * g), c = *(const u32x4*)(xq1 + tok * 512 + h * 128 + 32 * ks + 8 * g);
;         u32x4 w; w.x = pk2(bf_lo(a.x) + bf_lo(c.x), bf_hi(a.x) + bf_hi(c.x)); w.y = pk2(bf_lo(a.y) + bf_lo(c.y), bf_hi(a.y) + bf_hi(c.y));
;         w.z = pk2(bf_lo(a.z) + bf_lo(c.z), bf_hi(a.z) + bf_hi(c.z)); w.w = pk2(bf_lo(a.w) + bf_lo(c.w), bf_hi(a.w) + bf_hi(c.w));
;         qf[ks] = as_bf16x8(w);
;     }
; __device__ __forceinline__ void xattn_sample_block(LAS unsigned char* lds, const bf16_t* xq, const bf16_t* xq1, const float* mk, const float* mv, bf16_t* xo, int it, int tid) {
;     ...
;             float m = ml[(0 * 8 + t) * 2];
; #pragma unroll
;             for (int w = 1; w < 4; ++w) m = fmaxf(m, ml[(w * 8 + t) * 2]);
;             float den = 0.f; f32x2 acc = {0.f, 0.f};
; #pragma unroll
;             for (int w = 0; w < 4; ++w) {
;                 const float sc = __expf(ml[(w * 8 + t) * 2] - m);
;                 den += sc * ml[(w * 8 + t) * 2 + 1];
;                 acc += sc * *(const LAS f32x2*)(po + (w * 8 + t) * 128 + 2 * lane);
;             }
;             const float inv = 1.0f / den;
;             *(unsigned*)(xo + (tok0 + t) * 512 + h * 128 + 2 * lane) = pk2(acc[0] * inv, acc[1] * inv);
;         }
	v_max3_f32 v36, v2, v4, v6
	v_max3_f32 v36, v36, v8, v10
	v_max3_f32 v36, v36, v12, v14
	v_max_f32_e32 v36, v36, v16
	v_mov_b32_e32 v37, 0
	v_mov_b32_e32 v38, 0
	v_mov_b32_e32 v39, 0
	v_sub_f32_e32 v40, v2, v36
	v_mul_f32_e32 v40, 0x3fb8aa3b, v40
	v_exp_f32_e32 v40, v40
	s_nop 0
	v_fmac_f32_e32 v37, v40, v3
	v_fmac_f32_e32 v38, v40, v18
	v_fmac_f32_e32 v39, v40, v19
	v_sub_f32_e32 v40, v4, v36
	v_mul_f32_e32 v40, 0x3fb8aa3b, v40
	v_exp_f32_e32 v40, v40
	s_nop 0
	v_fmac_f32_e32 v37, v40, v5
	v_fmac_f32_e32 v38, v40, v20
	v_fmac_f32_e32 v39, v40, v21
	v_sub_f32_e32 v40, v6, v36
	v_mul_f32_e32 v40, 0x3fb8aa3b, v40
	v_exp_f32_e32 v40, v40
	s_nop 0
	v_fmac_f32_e32 v37, v40, v7
	v_fmac_f32_e32 v38, v40, v22
	v_fmac_f32_e32 v39, v40, v23
	v_sub_f32_e32 v40, v8, v36
	v_mul_f32_e32 v40, 0x3fb8aa3b, v40
	v_exp_f32_e32 v40, v40
	s_nop 0
	v_fmac_f32_e32 v37, v40, v9
	v_fmac_f32_e32 v38, v40, v24
	v_fmac_f32_e32 v39, v40, v25
	v_sub_f32_e32 v40, v10, v36
	v_mul_f32_e32 v40, 0x3fb8aa3b, v40
	v_exp_f32_e32 v40, v40
	s_nop 0
	v_fmac_f32_e32 v37, v40, v11
	v_fmac_f32_e32 v38, v40, v26
	v_fmac_f32_e32 v39, v40, v27
	v_sub_f32_e32 v40, v12, v36
	v_mul_f32_e32 v40, 0x3fb8aa3b, v40
	v_exp_f32_e32 v40, v40
	s_nop 0
	v_fmac_f32_e32 v37, v40, v13
	v_fmac_f32_e32 v38, v40, v28
	v_fmac_f32_e32 v39, v40, v29
	v_sub_f32_e32 v40, v14, v36
	v_mul_f32_e32 v40, 0x3fb8aa3b, v40
	v_exp_f32_e32 v40, v40
	s_nop 0
	v_fmac_f32_e32 v37, v40, v15
	v_fmac_f32_e32 v38, v40, v30
	v_fmac_f32_e32 v39, v40, v31
	v_sub_f32_e32 v40, v16, v36
	v_mul_f32_e32 v40, 0x3fb8aa3b, v40
	v_exp_f32_e32 v40, v40
	s_nop 0
	v_fmac_f32_e32 v37, v40, v17
	v_fmac_f32_e32 v38, v40, v32
	v_fmac_f32_e32 v39, v40, v33
	v_div_scale_f32 v40, s[6:7], v37, v37, 1.0
	v_rcp_f32_e32 v41, v40
	s_nop 0
	v_fma_f32 v42, -v40, v41, 1.0
	v_fmac_f32_e32 v41, v42, v41
	v_div_scale_f32 v42, vcc, 1.0, v37, 1.0
	v_mul_f32_e32 v43, v42, v41
	v_fma_f32 v44, -v40, v43, v42
	v_fmac_f32_e32 v43, v44, v41
	v_fma_f32 v40, -v40, v43, v42
	v_div_fmas_f32 v40, v40, v41, v43
	v_div_fixup_f32 v40, v40, v37, 1.0
	v_mul_f32_e32 v38, v38, v40
	v_mul_f32_e32 v39, v39, v40
	v_cvt_pk_bf16_f32 v38, v38, v39
	s_lshl_b32 s5, s4, 3
	s_addk_i32 s5, 0x2000
	s_lshl_b32 s5, s5, 10
	s_lshl_b32 s6, s31, 8
	s_add_i32 s5, s5, s6
	s_add_u32 s24, s14, s5
	s_addc_u32 s25, s15, 0
	v_lshlrev_b32_e32 v60, 10, v58
	v_lshl_add_u32 v60, v59, 2, v60
	global_store_dword v60, v38, s[24:25]
	v_readlane_b32 s5, v254, 28
	s_nop 1
	s_add_i32 s28, s28, s5
	s_cmpk_lt_i32 s28, 0x80
	s_waitcnt lgkmcnt(0)
	s_barrier
	s_cbranch_scc1 .Lxs_item
	v_readlane_b32 s21, v254, 29
.LBB0_1402:
	s_mov_b32 s6, s26
	s_movk_i32 s7, 0xff
	s_cmpk_eq_i32 s88, 0x100
	s_cselect_b32 s7, 0x7f, s7
	s_cmp_gt_i32 s6, s7
	s_cbranch_scc1 .LBB0_1405
	s_cmpk_eq_i32 s88, 0x100
	s_cbranch_scc0 .Lxp_nomap
	s_lshr_b32 s4, s26, 2
	s_lshl_b32 s4, s4, 3
	s_and_b32 s5, s26, 3
	s_add_i32 s6, s4, s5
.Lxp_nomap:
	s_mov_b32 s28, 0
	v_lshrrev_b32_e32 v8, 4, v139
	v_and_b32_e32 v9, 15, v139
	v_lshlrev_b32_e32 v9, 4, v9
	v_lshl_add_u32 v58, v8, 13, v9
	v_bfe_u32 v0, v8, 2, 1
	v_lshlrev_b32_e32 v0, 4, v0
	v_lshrrev_b32_e32 v136, 3, v8
	v_lshl_add_u32 v0, v136, 2, v0
	v_and_b32_e32 v136, 3, v8
	v_add_u32_e32 v0, v0, v136
	v_mul_u32_u24_e32 v0, 272, v0
	v_add_u32_e32 v59, v0, v9
	v_lshrrev_b32_e32 v8, 5, v139
	v_and_b32_e32 v9, 31, v139
	v_lshlrev_b32_e32 v9, 4, v9
	v_lshl_add_u32 v60, v8, 9, v9
	v_mul_u32_u24_e32 v0, 528, v8
	v_add_u32_e32 v61, v0, v9
	v_add_u32_e32 v61, 0x11000, v61
	v_and_b32_e32 v0, 15, v215
	v_lshrrev_b32_e32 v8, 4, v215
	v_lshlrev_b32_e32 v9, 4, v8
	v_lshl_add_u32 v2, v0, 10, v9
	v_lshlrev_b32_e32 v5, 3, v8
	v_lshl_add_u32 v5, v0, 10, v5
	v_mul_u32_u24_e32 v3, 272, v0
	v_add_u32_e32 v3, v3, v9
	v_mul_u32_u24_e32 v4, 528, v0
	v_add_u32_e32 v4, v4, v9
	v_add_u32_e32 v4, 0x11000, v4
	v_xor_b32_e32 v6, 16, v215
	v_lshlrev_b32_e32 v6, 2, v6
	v_xor_b32_e32 v7, 32, v215
	v_lshlrev_b32_e32 v7, 2, v7
.Lxp_pair:
	s_and_b32 s7, s6, 3
	s_lshr_b32 s4, s6, 2
	s_lshr_b32 s5, s4, 5
	s_lshl_b32 s4, s4, 3
	s_ashr_i32 s16, s27, 6
	s_add_i32 s4, s4, s16
	s_lshl_b32 s80, s7, 8
	s_lshl_b32 s4, s4, 14
	s_add_i32 s4, s4, s80
	s_add_u32 s22, s10, s4
	s_addc_u32 s23, s11, 0
	s_add_u32 s24, s12, s4
	s_addc_u32 s25, s13, 0
	global_load_dwordx4 v[26:29], v2, s[22:23] offset:0
	global_load_dwordx4 v[30:33], v2, s[22:23] offset:64
	global_load_dwordx4 v[34:37], v2, s[22:23] offset:128
	global_load_dwordx4 v[38:41], v2, s[22:23] offset:192
	global_load_dwordx4 v[42:45], v2, s[24:25] offset:0
	global_load_dwordx4 v[46:49], v2, s[24:25] offset:64
	global_load_dwordx4 v[50:53], v2, s[24:25] offset:128
	global_load_dwordx4 v[54:57], v2, s[24:25] offset:192
	s_cmp_lg_u32 s28, 0
	s_cbranch_scc1 .Lxp_nostage
; #define MFMA16(a, b, c) __builtin_amdgcn_mfma_f32_16x16x32_bf16((a), (b), (c), 0, 0, 0)
; __device__ __forceinline__ float bf_lo(unsigned w) { return __uint_as_float(w << 16); }
; __device__ __forceinline__ float bf_hi(unsigned w) { return __uint_as_float(w & 0xffff0000u); }
; __device__ __forceinline__ unsigned pk2(float lo, float hi) { return pg8::cvt_pk_bf16(lo, hi); }
; __device__ __forceinline__ void xattn_prompt_item(const bf16_t* xq, const bf16_t* xq1, const bf16_t* memkv, const bf16_t* memvt, bf16_t* xo, int l, int it, int lane) {
;     ...
;     for (int ks = 0; ks < 4; ++ks) {
;         const u32x4 a = *(const u32x4*)(xq + tok * 512 + h * 128 + 32 * ks + 8 * g), c = *(const u32x4*)(xq1 + tok * 512 + h * 128 + 32 * ks + 8 * g);
;         u32x4 w; w.x = pk2(bf_lo(a.x) + bf_lo(c.x), bf_hi(a.x) + bf_hi(c.x)); w.y = pk2(bf_lo(a.y) + bf_lo(c.y), bf_hi(a.y) + bf_hi(c.y));
;         w.z = pk2(bf_lo(a.z) + bf_lo(c.z), bf_hi(a.z) + bf_hi(c.z)); w.w = pk2(bf_lo(a.w) + bf_lo(c.w), bf_hi(a.w) + bf_hi(c.w));
;         qf[ks] = as_bf16x8(w);
;     }
;     f32x4 sc[16];
;     float mx = -1e30f;
; #pragma unroll
;     for (int kt = 0; kt < 16; ++kt) {
;         const bf16_t* kp = memkv + ((size_t)b * 256 + 16 * kt + l15) * 4096 + l * 1024 + h * 128 + 8 * g;
;         f32x4 a = {0.f, 0.f, 0.f, 0.f};
; #pragma unroll
;         for (int ks = 0; ks < 4; ++ks) a = MFMA16(*(const bf16x8*)(kp + 32 * ks), qf[ks], a);
	v_readlane_b32 s18, v254, 42
	v_readlane_b32 s19, v254, 43
	v_readlane_b32 s20, v254, 38
	s_nop 0
	s_lshl_b32 s21, s20, 11
	s_add_i32 s21, s21, s80
	s_lshl_b32 s16, s5, 21
	s_add_i32 s21, s21, s16
	s_add_u32 s16, s18, 0x28c28000
	s_addc_u32 s17, s19, 0
	s_add_u32 s16, s16, s21
	s_addc_u32 s17, s17, 0
	s_lshl_b32 s20, s20, 1
	s_add_i32 s20, s20, s5
	s_lshl_b32 s20, s20, 18
	s_lshl_b32 s21, s7, 16
	s_add_i32 s21, s21, s20
	s_add_u32 s20, s18, 0x29028000
	s_addc_u32 s19, s19, 0
	s_add_u32 s20, s20, s21
	s_addc_u32 s21, s19, 0
	s_add_u32 s4, s14, s4
	s_addc_u32 s5, s15, 0
	global_load_dwordx4 v[146:149], v58, s[16:17]
	s_add_u32 s16, s16, 0x40000
	s_addc_u32 s17, s17, 0
	global_load_dwordx4 v[150:153], v58, s[16:17]
	s_add_u32 s16, s16, 0x40000
	s_addc_u32 s17, s17, 0
	global_load_dwordx4 v[154:157], v58, s[16:17]
	s_add_u32 s16, s16, 0x40000
	s_addc_u32 s17, s17, 0
	global_load_dwordx4 v[158:161], v58, s[16:17]
	s_add_u32 s16, s16, 0x40000
	s_addc_u32 s17, s17, 0
	global_load_dwordx4 v[162:165], v58, s[16:17]
	s_add_u32 s16, s16, 0x40000
	s_addc_u32 s17, s17, 0
	global_load_dwordx4 v[166:169], v58, s[16:17]
	s_add_u32 s16, s16, 0x40000
	s_addc_u32 s17, s17, 0
	global_load_dwordx4 v[170:173], v58, s[16:17]
	s_add_u32 s16, s16, 0x40000
	s_addc_u32 s17, s17, 0
	global_load_dwordx4 v[174:177], v58, s[16:17]
	global_load_dwordx4 v[178:181], v60, s[20:21]
	s_add_u32 s20, s20, 0x2000
	s_addc_u32 s21, s21, 0
	global_load_dwordx4 v[182:185], v60, s[20:21]
	s_add_u32 s20, s20, 0x2000
	s_addc_u32 s21, s21, 0
	global_load_dwordx4 v[186:189], v60, s[20:21]
	s_add_u32 s20, s20, 0x2000
	s_addc_u32 s21, s21, 0
	global_load_dwordx4 v[190:193], v60, s[20:21]
	s_add_u32 s20, s20, 0x2000
	s_addc_u32 s21, s21, 0
	global_load_dwordx4 v[194:197], v60, s[20:21]
	s_add_u32 s20, s20, 0x2000
	s_addc_u32 s21, s21, 0
	global_load_dwordx4 v[198:201], v60, s[20:21]
	s_add_u32 s20, s20, 0x2000
	s_addc_u32 s21, s21, 0
	global_load_dwordx4 v[202:205], v60, s[20:21]
	s_add_u32 s20, s20, 0x2000
	s_addc_u32 s21, s21, 0
	global_load_dwordx4 v[206:209], v60, s[20:21]
	s_waitcnt vmcnt(16)
	v_lshlrev_b32_e32 v8, 16, v26
	v_and_b32_e32 v9, 0xffff0000, v26
	v_lshlrev_b32_e32 v136, 16, v42
	v_and_b32_e32 v137, 0xffff0000, v42
	v_pk_add_f32 v[8:9], v[8:9], v[136:137]
	v_cvt_pk_bf16_f32 v10, v8, v9
	v_lshlrev_b32_e32 v8, 16, v27
	v_and_b32_e32 v9, 0xffff0000, v27
	v_lshlrev_b32_e32 v136, 16, v43
	v_and_b32_e32 v137, 0xffff0000, v43
	v_pk_add_f32 v[8:9], v[8:9], v[136:137]
	v_cvt_pk_bf16_f32 v11, v8, v9
	v_lshlrev_b32_e32 v8, 16, v28
	v_and_b32_e32 v9, 0xffff0000, v28
	v_lshlrev_b32_e32 v136, 16, v44
	v_and_b32_e32 v137, 0xffff0000, v44
	v_pk_add_f32 v[8:9], v[8:9], v[136:137]
	v_cvt_pk_bf16_f32 v12, v8, v9
	v_lshlrev_b32_e32 v8, 16, v29
	v_and_b32_e32 v9, 0xffff0000, v29
	v_lshlrev_b32_e32 v136, 16, v45
	v_and_b32_e32 v137, 0xffff0000, v45
	v_pk_add_f32 v[8:9], v[8:9], v[136:137]
	v_cvt_pk_bf16_f32 v13, v8, v9
	v_lshlrev_b32_e32 v8, 16, v30
	v_and_b32_e32 v9, 0xffff0000, v30
	v_lshlrev_b32_e32 v136, 16, v46
	v_and_b32_e32 v137, 0xffff0000, v46
	v_pk_add_f32 v[8:9], v[8:9], v[136:137]
	v_cvt_pk_bf16_f32 v14, v8, v9
	v_lshlrev_b32_e32 v8, 16, v31
	v_and_b32_e32 v9, 0xffff0000, v31
	v_lshlrev_b32_e32 v136, 16, v47
	v_and_b32_e32 v137, 0xffff0000, v47
	v_pk_add_f32 v[8:9], v[8:9], v[136:137]
	v_cvt_pk_bf16_f32 v15, v8, v9
	v_lshlrev_b32_e32 v8, 16, v32
	v_and_b32_e32 v9, 0xffff0000, v32
	v_lshlrev_b32_e32 v136, 16, v48
	v_and_b32_e32 v137, 0xffff0000, v48
	v_pk_add_f32 v[8:9], v[8:9], v[136:137]
	v_cvt_pk_bf16_f32 v16, v8, v9
	v_lshlrev_b32_e32 v8, 16, v33
	v_and_b32_e32 v9, 0xffff0000, v33
	v_lshlrev_b32_e32 v136, 16, v49
	v_and_b32_e32 v137, 0xffff0000, v49
	v_pk_add_f32 v[8:9], v[8:9], v[136:137]
	v_cvt_pk_bf16_f32 v17, v8, v9
	v_lshlrev_b32_e32 v8, 16, v34
	v_and_b32_e32 v9, 0xffff0000, v34
	v_lshlrev_b32_e32 v136, 16, v50
	v_and_b32_e32 v137, 0xffff0000, v50
	v_pk_add_f32 v[8:9], v[8:9], v[136:137]
	v_cvt_pk_bf16_f32 v18, v8, v9
	v_lshlrev_b32_e32 v8, 16, v35
	v_and_b32_e32 v9, 0xffff0000, v35
	v_lshlrev_b32_e32 v136, 16, v51
	v_and_b32_e32 v137, 0xffff0000, v51
	v_pk_add_f32 v[8:9], v[8:9], v[136:137]
	v_cvt_pk_bf16_f32 v19, v8, v9
	v_lshlrev_b32_e32 v8, 16, v36
	v_and_b32_e32 v9, 0xffff0000, v36
	v_lshlrev_b32_e32 v136, 16, v52
	v_and_b32_e32 v137, 0xffff0000, v52
	v_pk_add_f32 v[8:9], v[8:9], v[136:137]
	v_cvt_pk_bf16_f32 v20, v8, v9
	v_lshlrev_b32_e32 v8, 16, v37
	v_and_b32_e32 v9, 0xffff0000, v37
	v_lshlrev_b32_e32 v136, 16, v53
	v_and_b32_e32 v137, 0xffff0000, v53
	v_pk_add_f32 v[8:9], v[8:9], v[136:137]
	v_cvt_pk_bf16_f32 v21, v8, v9
	v_lshlrev_b32_e32 v8, 16, v38
	v_and_b32_e32 v9, 0xffff0000, v38
	v_lshlrev_b32_e32 v136, 16, v54
	v_and_b32_e32 v137, 0xffff0000, v54
	v_pk_add_f32 v[8:9], v[8:9], v[136:137]
	v_cvt_pk_bf16_f32 v22, v8, v9
	v_lshlrev_b32_e32 v8, 16, v39
	v_and_b32_e32 v9, 0xffff0000, v39
	v_lshlrev_b32_e32 v136, 16, v55
	v_and_b32_e32 v137, 0xffff0000, v55
	v_pk_add_f32 v[8:9], v[8:9], v[136:137]
	v_cvt_pk_bf16_f32 v23, v8, v9
	v_lshlrev_b32_e32 v8, 16, v40
	v_and_b32_e32 v9, 0xffff0000, v40
	v_lshlrev_b32_e32 v136, 16, v56
	v_and_b32_e32 v137, 0xffff0000, v56
	v_pk_add_f32 v[8:9], v[8:9], v[136:137]
	v_cvt_pk_bf16_f32 v24, v8, v9
	v_lshlrev_b32_e32 v8, 16, v41
	v_and_b32_e32 v9, 0xffff0000, v41
	v_lshlrev_b32_e32 v136, 16, v57
	v_and_b32_e32 v137, 0xffff0000, v57
	v_pk_add_f32 v[8:9], v[8:9], v[136:137]
	v_cvt_pk_bf16_f32 v25, v8, v9
	s_waitcnt vmcnt(15)
	ds_write_b128 v59, v[146:149] offset:0
	s_waitcnt vmcnt(14)
	ds_write_b128 v59, v[150:153] offset:8704
	s_waitcnt vmcnt(13)
	ds_write_b128 v59, v[154:157] offset:17408
	s_waitcnt vmcnt(12)
	ds_write_b128 v59, v[158:161] offset:26112
	s_waitcnt vmcnt(11)
	ds_write_b128 v59, v[162:165] offset:34816
	s_waitcnt vmcnt(10)
	ds_write_b128 v59, v[166:169] offset:43520
	s_waitcnt vmcnt(9)
	ds_write_b128 v59, v[170:173] offset:52224
	s_waitcnt vmcnt(8)
	ds_write_b128 v59, v[174:177] offset:60928
	s_waitcnt vmcnt(7)
	ds_write_b128 v61, v[178:181] offset:0
	s_waitcnt vmcnt(6)
	ds_write_b128 v61, v[182:185] offset:8448
	s_waitcnt vmcnt(5)
	ds_write_b128 v61, v[186:189] offset:16896
	s_waitcnt vmcnt(4)
	ds_write_b128 v61, v[190:193] offset:25344
	s_waitcnt vmcnt(3)
	ds_write_b128 v61, v[194:197] offset:33792
	s_waitcnt vmcnt(2)
	ds_write_b128 v61, v[198:201] offset:42240
	s_waitcnt vmcnt(1)
	ds_write_b128 v61, v[202:205] offset:50688
	s_waitcnt vmcnt(0)
	ds_write_b128 v61, v[206:209] offset:59136
	s_waitcnt lgkmcnt(0)
	s_barrier
	s_branch .Lxp_go
; #define MFMA16(a, b, c) __builtin_amdgcn_mfma_f32_16x16x32_bf16((a), (b), (c), 0, 0, 0)
; __device__ __forceinline__ float bf_lo(unsigned w) { return __uint_as_float(w << 16); }
; __device__ __forceinline__ float bf_hi(unsigned w) { return __uint_as_float(w & 0xffff0000u); }
; __device__ __forceinline__ unsigned pk2(float lo, float hi) { return pg8::cvt_pk_bf16(lo, hi); }
; __device__ __forceinline__ void xattn_prompt_item(const bf16_t* xq, const bf16_t* xq1, const bf16_t* memkv, const bf16_t* memvt, bf16_t* xo, int l, int it, int lane) {
;     ...
;     for (int ks = 0; ks < 4; ++ks) {
;         const u32x4 a = *(const u32x4*)(xq + tok * 512 + h * 128 + 32 * ks + 8 * g), c = *(const u32x4*)(xq1 + tok * 512 + h * 128 + 32 * ks + 8 * g);
;         u32x4 w; w.x = pk2(bf_lo(a.x) + bf_lo(c.x), bf_hi(a.x) + bf_hi(c.x)); w.y = pk2(bf_lo(a.y) + bf_lo(c.y), bf_hi(a.y) + bf_hi(c.y));
;         w.z = pk2(bf_lo(a.z) + bf_lo(c.z), bf_hi(a.z) + bf_hi(c.z)); w.w = pk2(bf_lo(a.w) + bf_lo(c.w), bf_hi(a.w) + bf_hi(c.w));
;         qf[ks] = as_bf16x8(w);
;     }
;     f32x4 sc[16];
;     float mx = -1e30f;
; #pragma unroll
;     for (int kt = 0; kt < 16; ++kt) {
;         const bf16_t* kp = memkv + ((size_t)b * 256 + 16 * kt + l15) * 4096 + l * 1024 + h * 128 + 8 * g;
;         f32x4 a = {0.f, 0.f, 0.f, 0.f};
; #pragma unroll
;         for (int ks = 0; ks < 4; ++ks) a = MFMA16(*(const bf16x8*)(kp + 32 * ks), qf[ks], a);
;         a = a * 0.08838834764831845f;
;         sc[kt] = a; mx = fmaxf(fmaxf(mx, fmaxf(a[0], a[1])), fmaxf(a[2], a[3]));
.Lxp_nostage:
	s_add_u32 s4, s14, s4
	s_addc_u32 s5, s15, 0
	s_waitcnt vmcnt(0)
	v_lshlrev_b32_e32 v8, 16, v26
	v_and_b32_e32 v9, 0xffff0000, v26
	v_lshlrev_b32_e32 v136, 16, v42
	v_and_b32_e32 v137, 0xffff0000, v42
	v_pk_add_f32 v[8:9], v[8:9], v[136:137]
	v_cvt_pk_bf16_f32 v10, v8, v9
	v_lshlrev_b32_e32 v8, 16, v27
	v_and_b32_e32 v9, 0xffff0000, v27
	v_lshlrev_b32_e32 v136, 16, v43
	v_and_b32_e32 v137, 0xffff0000, v43
	v_pk_add_f32 v[8:9], v[8:9], v[136:137]
	v_cvt_pk_bf16_f32 v11, v8, v9
	v_lshlrev_b32_e32 v8, 16, v28
	v_and_b32_e32 v9, 0xffff0000, v28
	v_lshlrev_b32_e32 v136, 16, v44
	v_and_b32_e32 v137, 0xffff0000, v44
	v_pk_add_f32 v[8:9], v[8:9], v[136:137]
	v_cvt_pk_bf16_f32 v12, v8, v9
	v_lshlrev_b32_e32 v8, 16, v29
	v_and_b32_e32 v9, 0xffff0000, v29
	v_lshlrev_b32_e32 v136, 16, v45
	v_and_b32_e32 v137, 0xffff0000, v45
	v_pk_add_f32 v[8:9], v[8:9], v[136:137]
	v_cvt_pk_bf16_f32 v13, v8, v9
	v_lshlrev_b32_e32 v8, 16, v30
	v_and_b32_e32 v9, 0xffff0000, v30
	v_lshlrev_b32_e32 v136, 16, v46
	v_and_b32_e32 v137, 0xffff0000, v46
	v_pk_add_f32 v[8:9], v[8:9], v[136:137]
	v_cvt_pk_bf16_f32 v14, v8, v9
	v_lshlrev_b32_e32 v8, 16, v31
	v_and_b32_e32 v9, 0xffff0000, v31
	v_lshlrev_b32_e32 v136, 16, v47
	v_and_b32_e32 v137, 0xffff0000, v47
	v_pk_add_f32 v[8:9], v[8:9], v[136:137]
	v_cvt_pk_bf16_f32 v15, v8, v9
	v_lshlrev_b32_e32 v8, 16, v32
	v_and_b32_e32 v9, 0xffff0000, v32
	v_lshlrev_b32_e32 v136, 16, v48
	v_and_b32_e32 v137, 0xffff0000, v48
	v_pk_add_f32 v[8:9], v[8:9], v[136:137]
	v_cvt_pk_bf16_f32 v16, v8, v9
	v_lshlrev_b32_e32 v8, 16, v33
	v_and_b32_e32 v9, 0xffff0000, v33
	v_lshlrev_b32_e32 v136, 16, v49
	v_and_b32_e32 v137, 0xffff0000, v49
	v_pk_add_f32 v[8:9], v[8:9], v[136:137]
	v_cvt_pk_bf16_f32 v17, v8, v9
	v_lshlrev_b32_e32 v8, 16, v34
	v_and_b32_e32 v9, 0xffff0000, v34
	v_lshlrev_b32_e32 v136, 16, v50
	v_and_b32_e32 v137, 0xffff0000, v50
	v_pk_add_f32 v[8:9], v[8:9], v[136:137]
	v_cvt_pk_bf16_f32 v18, v8, v9
	v_lshlrev_b32_e32 v8, 16, v35
	v_and_b32_e32 v9, 0xffff0000, v35
	v_lshlrev_b32_e32 v136, 16, v51
	v_and_b32_e32 v137, 0xffff0000, v51
	v_pk_add_f32 v[8:9], v[8:9], v[136:137]
	v_cvt_pk_bf16_f32 v19, v8, v9
	v_lshlrev_b32_e32 v8, 16, v36
	v_and_b32_e32 v9, 0xffff0000, v36
	v_lshlrev_b32_e32 v136, 16, v52
	v_and_b32_e32 v137, 0xffff0000, v52
	v_pk_add_f32 v[8:9], v[8:9], v[136:137]
	v_cvt_pk_bf16_f32 v20, v8, v9
	v_lshlrev_b32_e32 v8, 16, v37
	v_and_b32_e32 v9, 0xffff0000, v37
	v_lshlrev_b32_e32 v136, 16, v53
	v_and_b32_e32 v137, 0xffff0000, v53
	v_pk_add_f32 v[8:9], v[8:9], v[136:137]
	v_cvt_pk_bf16_f32 v21, v8, v9
	v_lshlrev_b32_e32 v8, 16, v38
	v_and_b32_e32 v9, 0xffff0000, v38
	v_lshlrev_b32_e32 v136, 16, v54
	v_and_b32_e32 v137, 0xffff0000, v54
	v_pk_add_f32 v[8:9], v[8:9], v[136:137]
	v_cvt_pk_bf16_f32 v22, v8, v9
	v_lshlrev_b32_e32 v8, 16, v39
	v_and_b32_e32 v9, 0xffff0000, v39
	v_lshlrev_b32_e32 v136, 16, v55
	v_and_b32_e32 v137, 0xffff0000, v55
	v_pk_add_f32 v[8:9], v[8:9], v[136:137]
	v_cvt_pk_bf16_f32 v23, v8, v9
	v_lshlrev_b32_e32 v8, 16, v40
	v_and_b32_e32 v9, 0xffff0000, v40
	v_lshlrev_b32_e32 v136, 16, v56
	v_and_b32_e32 v137, 0xffff0000, v56
	v_pk_add_f32 v[8:9], v[8:9], v[136:137]
	v_cvt_pk_bf16_f32 v24, v8, v9
	v_lshlrev_b32_e32 v8, 16, v41
	v_and_b32_e32 v9, 0xffff0000, v41
	v_lshlrev_b32_e32 v136, 16, v57
	v_and_b32_e32 v137, 0xffff0000, v57
	v_pk_add_f32 v[8:9], v[8:9], v[136:137]
	v_cvt_pk_bf16_f32 v25, v8, v9
.Lxp_go:
	v_mov_b32_e32 v63, 0xf149f2ca
	ds_read_b128 v[146:149], v3 offset:0
	ds_read_b128 v[150:153], v3 offset:64
	ds_read_b128 v[154:157], v3 offset:128
	ds_read_b128 v[158:161], v3 offset:192
	ds_read_b128 v[162:165], v3 offset:4352
	ds_read_b128 v[166:169], v3 offset:4416
	ds_read_b128 v[170:173], v3 offset:4480
	ds_read_b128 v[174:177], v3 offset:4544
	ds_read_b128 v[178:181], v3 offset:8704
	ds_read_b128 v[182:185], v3 offset:8768
	ds_read_b128 v[186:189], v3 offset:8832
	ds_read_b128 v[190:193], v3 offset:8896
	s_waitcnt lgkmcnt(4)
	v_mfma_f32_16x16x32_bf16 v[64:67], v[146:149], v[10:13], 0
	v_mfma_f32_16x16x32_bf16 v[68:71], v[162:165], v[10:13], 0
	ds_read_b128 v[194:197], v3 offset:13056
	v_mfma_f32_16x16x32_bf16 v[64:67], v[150:153], v[14:17], v[64:67]
	v_mfma_f32_16x16x32_bf16 v[68:71], v[166:169], v[14:17], v[68:71]
	ds_read_b128 v[198:201], v3 offset:13120
	v_mfma_f32_16x16x32_bf16 v[64:67], v[154:157], v[18:21], v[64:67]
	v_mfma_f32_16x16x32_bf16 v[68:71], v[170:173], v[18:21], v[68:71]
	ds_read_b128 v[202:205], v3 offset:13184
	v_mfma_f32_16x16x32_bf16 v[64:67], v[158:161], v[22:25], v[64:67]
	v_mfma_f32_16x16x32_bf16 v[68:71], v[174:177], v[22:25], v[68:71]
	ds_read_b128 v[206:209], v3 offset:13248
	ds_read_b128 v[146:149], v3 offset:17408
	ds_read_b128 v[150:153], v3 offset:17472
	ds_read_b128 v[154:157], v3 offset:17536
	ds_read_b128 v[158:161], v3 offset:17600
	s_waitcnt lgkmcnt(4)
	v_mfma_f32_16x16x32_bf16 v[72:75], v[178:181], v[10:13], 0
	v_mfma_f32_16x16x32_bf16 v[76:79], v[194:197], v[10:13], 0
	ds_read_b128 v[162:165], v3 offset:21760
	v_mfma_f32_16x16x32_bf16 v[72:75], v[182:185], v[14:17], v[72:75]
	v_mfma_f32_16x16x32_bf16 v[76:79], v[198:201], v[14:17], v[76:79]
	ds_read_b128 v[166:169], v3 offset:21824
	v_mfma_f32_16x16x32_bf16 v[72:75], v[186:189], v[18:21], v[72:75]
	v_mfma_f32_16x16x32_bf16 v[76:79], v[202:205], v[18:21], v[76:79]
	ds_read_b128 v[170:173], v3 offset:21888
	v_mfma_f32_16x16x32_bf16 v[72:75], v[190:193], v[22:25], v[72:75]
	v_mfma_f32_16x16x32_bf16 v[76:79], v[206:209], v[22:25], v[76:79]
	ds_read_b128 v[174:177], v3 offset:21952
	v_pk_mul_f32 v[64:65], v[64:65], s[86:87] op_sel_hi:[1,0]
	v_pk_mul_f32 v[66:67], v[66:67], s[86:87] op_sel_hi:[1,0]
	v_max3_f32 v63, v63, v64, v65
	v_max3_f32 v63, v63, v66, v67
	v_pk_mul_f32 v[68:69], v[68:69], s[86:87] op_sel_hi:[1,0]
	v_pk_mul_f32 v[70:71], v[70:71], s[86:87] op_sel_hi:[1,0]
	v_max3_f32 v63, v63, v68, v69
	v_max3_f32 v63, v63, v70, v71
	ds_read_b128 v[178:181], v3 offset:26112
	ds_read_b128 v[182:185], v3 offset:26176
	ds_read_b128 v[186:189], v3 offset:26240
	ds_read_b128 v[190:193], v3 offset:26304
	s_waitcnt lgkmcnt(4)
; #define MFMA16(a, b, c) __builtin_amdgcn_mfma_f32_16x16x32_bf16((a), (b), (c), 0, 0, 0)
; __device__ __forceinline__ void xattn_prompt_item(const bf16_t* xq, const bf16_t* xq1, const bf16_t* memkv, const bf16_t* memvt, bf16_t* xo, int l, int it, int lane) {
;     ...
; #pragma unroll
;     for (int kt = 0; kt < 16; ++kt) {
;         const bf16_t* kp = memkv + ((size_t)b * 256 + 16 * kt + l15) * 4096 + l * 1024 + h * 128 + 8 * g;
;         f32x4 a = {0.f, 0.f, 0.f, 0.f};
; #pragma unroll
;         for (int ks = 0; ks < 4; ++ks) a = MFMA16(*(const bf16x8*)(kp + 32 * ks), qf[ks], a);
;         a = a * 0.08838834764831845f;
;         sc[kt] = a; mx = fmaxf(fmaxf(mx, fmaxf(a[0], a[1])), fmaxf(a[2], a[3]));
;     }
	v_mfma_f32_16x16x32_bf16 v[80:83], v[146:149], v[10:13], 0
	v_mfma_f32_16x16x32_bf16 v[84:87], v[162:165], v[10:13], 0
	ds_read_b128 v[194:197], v3 offset:30464
	v_mfma_f32_16x16x32_bf16 v[80:83], v[150:153], v[14:17], v[80:83]
	v_mfma_f32_16x16x32_bf16 v[84:87], v[166:169], v[14:17], v[84:87]
	ds_read_b128 v[198:201], v3 offset:30528
	v_mfma_f32_16x16x32_bf16 v[80:83], v[154:157], v[18:21], v[80:83]
	v_mfma_f32_16x16x32_bf16 v[84:87], v[170:173], v[18:21], v[84:87]
	ds_read_b128 v[202:205], v3 offset:30592
	v_mfma_f32_16x16x32_bf16 v[80:83], v[158:161], v[22:25], v[80:83]
	v_mfma_f32_16x16x32_bf16 v[84:87], v[174:177], v[22:25], v[84:87]
	ds_read_b128 v[206:209], v3 offset:30656
	v_pk_mul_f32 v[72:73], v[72:73], s[86:87] op_sel_hi:[1,0]
	v_pk_mul_f32 v[74:75], v[74:75], s[86:87] op_sel_hi:[1,0]
	v_max3_f32 v63, v63, v72, v73
	v_max3_f32 v63, v63, v74, v75
	v_pk_mul_f32 v[76:77], v[76:77], s[86:87] op_sel_hi:[1,0]
	v_pk_mul_f32 v[78:79], v[78:79], s[86:87] op_sel_hi:[1,0]
	v_max3_f32 v63, v63, v76, v77
	v_max3_f32 v63, v63, v78, v79
	ds_read_b128 v[146:149], v3 offset:34816
	ds_read_b128 v[150:153], v3 offset:34880
	ds_read_b128 v[154:157], v3 offset:34944
	ds_read_b128 v[158:161], v3 offset:35008
	s_waitcnt lgkmcnt(4)
	v_mfma_f32_16x16x32_bf16 v[88:91], v[178:181], v[10:13], 0
	v_mfma_f32_16x16x32_bf16 v[92:95], v[194:197], v[10:13], 0
	ds_read_b128 v[162:165], v3 offset:39168
	v_mfma_f32_16x16x32_bf16 v[88:91], v[182:185], v[14:17], v[88:91]
	v_mfma_f32_16x16x32_bf16 v[92:95], v[198:201], v[14:17], v[92:95]
	ds_read_b128 v[166:169], v3 offset:39232
	v_mfma_f32_16x16x32_bf16 v[88:91], v[186:189], v[18:21], v[88:91]
	v_mfma_f32_16x16x32_bf16 v[92:95], v[202:205], v[18:21], v[92:95]
	ds_read_b128 v[170:173], v3 offset:39296
	v_mfma_f32_16x16x32_bf16 v[88:91], v[190:193], v[22:25], v[88:91]
	v_mfma_f32_16x16x32_bf16 v[92:95], v[206:209], v[22:25], v[92:95]
	ds_read_b128 v[174:177], v3 offset:39360
	v_pk_mul_f32 v[80:81], v[80:81], s[86:87] op_sel_hi:[1,0]
	v_pk_mul_f32 v[82:83], v[82:83], s[86:87] op_sel_hi:[1,0]
	v_max3_f32 v63, v63, v80, v81
	v_max3_f32 v63, v63, v82, v83
	v_pk_mul_f32 v[84:85], v[84:85], s[86:87] op_sel_hi:[1,0]
	v_pk_mul_f32 v[86:87], v[86:87], s[86:87] op_sel_hi:[1,0]
	v_max3_f32 v63, v63, v84, v85
	v_max3_f32 v63, v63, v86, v87
	ds_read_b128 v[178:181], v3 offset:43520
	ds_read_b128 v[182:185], v3 offset:43584
	ds_read_b128 v[186:189], v3 offset:43648
	ds_read_b128 v[190:193], v3 offset:43712
	s_waitcnt lgkmcnt(4)
	v_mfma_f32_16x16x32_bf16 v[96:99], v[146:149], v[10:13], 0
	v_mfma_f32_16x16x32_bf16 v[100:103], v[162:165], v[10:13], 0
	ds_read_b128 v[194:197], v3 offset:47872
	v_mfma_f32_16x16x32_bf16 v[96:99], v[150:153], v[14:17], v[96:99]
	v_mfma_f32_16x16x32_bf16 v[100:103], v[166:169], v[14:17], v[100:103]
	ds_read_b128 v[198:201], v3 offset:47936
	v_mfma_f32_16x16x32_bf16 v[96:99], v[154:157], v[18:21], v[96:99]
	v_mfma_f32_16x16x32_bf16 v[100:103], v[170:173], v[18:21], v[100:103]
	ds_read_b128 v[202:205], v3 offset:48000
	v_mfma_f32_16x16x32_bf16 v[96:99], v[158:161], v[22:25], v[96:99]
	v_mfma_f32_16x16x32_bf16 v[100:103], v[174:177], v[22:25], v[100:103]
	ds_read_b128 v[206:209], v3 offset:48064
	v_pk_mul_f32 v[88:89], v[88:89], s[86:87] op_sel_hi:[1,0]
	v_pk_mul_f32 v[90:91], v[90:91], s[86:87] op_sel_hi:[1,0]
	v_max3_f32 v63, v63, v88, v89
	v_max3_f32 v63, v63, v90, v91
	v_pk_mul_f32 v[92:93], v[92:93], s[86:87] op_sel_hi:[1,0]
	v_pk_mul_f32 v[94:95], v[94:95], s[86:87] op_sel_hi:[1,0]
	v_max3_f32 v63, v63, v92, v93
	v_max3_f32 v63, v63, v94, v95
	ds_read_b128 v[146:149], v3 offset:52224
	ds_read_b128 v[150:153], v3 offset:52288
	ds_read_b128 v[154:157], v3 offset:52352
	ds_read_b128 v[158:161], v3 offset:52416
	s_waitcnt lgkmcnt(4)
	v_mfma_f32_16x16x32_bf16 v[104:107], v[178:181], v[10:13], 0
	v_mfma_f32_16x16x32_bf16 v[108:111], v[194:197], v[10:13], 0
	ds_read_b128 v[162:165], v3 offset:56576
	v_mfma_f32_16x16x32_bf16 v[104:107], v[182:185], v[14:17], v[104:107]
	v_mfma_f32_16x16x32_bf16 v[108:111], v[198:201], v[14:17], v[108:111]
	ds_read_b128 v[166:169], v3 offset:56640
	v_mfma_f32_16x16x32_bf16 v[104:107], v[186:189], v[18:21], v[104:107]
	v_mfma_f32_16x16x32_bf16 v[108:111], v[202:205], v[18:21], v[108:111]
	ds_read_b128 v[170:173], v3 offset:56704
	v_mfma_f32_16x16x32_bf16 v[104:107], v[190:193], v[22:25], v[104:107]
	v_mfma_f32_16x16x32_bf16 v[108:111], v[206:209], v[22:25], v[108:111]
	ds_read_b128 v[174:177], v3 offset:56768
	v_pk_mul_f32 v[96:97], v[96:97], s[86:87] op_sel_hi:[1,0]
	v_pk_mul_f32 v[98:99], v[98:99], s[86:87] op_sel_hi:[1,0]
	v_max3_f32 v63, v63, v96, v97
	v_max3_f32 v63, v63, v98, v99
	v_pk_mul_f32 v[100:101], v[100:101], s[86:87] op_sel_hi:[1,0]
	v_pk_mul_f32 v[102:103], v[102:103], s[86:87] op_sel_hi:[1,0]
	v_max3_f32 v63, v63, v100, v101
	v_max3_f32 v63, v63, v102, v103
	ds_read_b128 v[178:181], v3 offset:60928
	ds_read_b128 v[182:185], v3 offset:60992
	ds_read_b128 v[186:189], v3 offset:61056
	ds_read_b128 v[190:193], v3 offset:61120
	s_waitcnt lgkmcnt(4)
; #define MFMA16(a, b, c) __builtin_amdgcn_mfma_f32_16x16x32_bf16((a), (b), (c), 0, 0, 0)
; __device__ __forceinline__ void xattn_prompt_item(const bf16_t* xq, const bf16_t* xq1, const bf16_t* memkv, const bf16_t* memvt, bf16_t* xo, int l, int it, int lane) {
;     ...
;     for (int kt = 0; kt < 16; ++kt) {
;         const bf16_t* kp = memkv + ((size_t)b * 256 + 16 * kt + l15) * 4096 + l * 1024 + h * 128 + 8 * g;
;         f32x4 a = {0.f, 0.f, 0.f, 0.f};
; #pragma unroll
;         for (int ks = 0; ks < 4; ++ks) a = MFMA16(*(const bf16x8*)(kp + 32 * ks), qf[ks], a);
;         a = a * 0.08838834764831845f;
;         sc[kt] = a; mx = fmaxf(fmaxf(mx, fmaxf(a[0], a[1])), fmaxf(a[2], a[3]));
;     }
;     mx = fmaxf(mx, __shfl_xor(mx, 16)); mx = fmaxf(mx, __shfl_xor(mx, 32));
;     float sum = 0.f;
; #pragma unroll
;     for (int kt = 0; kt < 16; ++kt)
; #pragma unroll
;         for (int j = 0; j < 4; ++j) { const float p = __expf(sc[kt][j] - mx); sc[kt][j] = p; sum += p; }
	v_mfma_f32_16x16x32_bf16 v[112:115], v[146:149], v[10:13], 0
	v_mfma_f32_16x16x32_bf16 v[116:119], v[162:165], v[10:13], 0
	ds_read_b128 v[194:197], v3 offset:65280
	v_mfma_f32_16x16x32_bf16 v[112:115], v[150:153], v[14:17], v[112:115]
	v_mfma_f32_16x16x32_bf16 v[116:119], v[166:169], v[14:17], v[116:119]
	ds_read_b128 v[198:201], v3 offset:65344
	v_mfma_f32_16x16x32_bf16 v[112:115], v[154:157], v[18:21], v[112:115]
	v_mfma_f32_16x16x32_bf16 v[116:119], v[170:173], v[18:21], v[116:119]
	ds_read_b128 v[202:205], v3 offset:65408
	v_mfma_f32_16x16x32_bf16 v[112:115], v[158:161], v[22:25], v[112:115]
	v_mfma_f32_16x16x32_bf16 v[116:119], v[174:177], v[22:25], v[116:119]
	ds_read_b128 v[206:209], v3 offset:65472
	v_pk_mul_f32 v[104:105], v[104:105], s[86:87] op_sel_hi:[1,0]
	v_pk_mul_f32 v[106:107], v[106:107], s[86:87] op_sel_hi:[1,0]
	v_max3_f32 v63, v63, v104, v105
	v_max3_f32 v63, v63, v106, v107
	v_pk_mul_f32 v[108:109], v[108:109], s[86:87] op_sel_hi:[1,0]
	v_pk_mul_f32 v[110:111], v[110:111], s[86:87] op_sel_hi:[1,0]
	v_max3_f32 v63, v63, v108, v109
	v_max3_f32 v63, v63, v110, v111
	ds_read_b128 v[146:149], v4 offset:0
	ds_read_b128 v[150:153], v4 offset:8448
	ds_read_b128 v[154:157], v4 offset:16896
	ds_read_b128 v[158:161], v4 offset:25344
	s_waitcnt lgkmcnt(4)
	v_mfma_f32_16x16x32_bf16 v[120:123], v[178:181], v[10:13], 0
	v_mfma_f32_16x16x32_bf16 v[124:127], v[194:197], v[10:13], 0
	ds_read_b128 v[162:165], v4 offset:33792
	v_mfma_f32_16x16x32_bf16 v[120:123], v[182:185], v[14:17], v[120:123]
	v_mfma_f32_16x16x32_bf16 v[124:127], v[198:201], v[14:17], v[124:127]
	ds_read_b128 v[166:169], v4 offset:42240
	v_mfma_f32_16x16x32_bf16 v[120:123], v[186:189], v[18:21], v[120:123]
	v_mfma_f32_16x16x32_bf16 v[124:127], v[202:205], v[18:21], v[124:127]
	ds_read_b128 v[170:173], v4 offset:50688
	v_mfma_f32_16x16x32_bf16 v[120:123], v[190:193], v[22:25], v[120:123]
	v_mfma_f32_16x16x32_bf16 v[124:127], v[206:209], v[22:25], v[124:127]
	ds_read_b128 v[174:177], v4 offset:59136
	v_pk_mul_f32 v[112:113], v[112:113], s[86:87] op_sel_hi:[1,0]
	v_pk_mul_f32 v[114:115], v[114:115], s[86:87] op_sel_hi:[1,0]
	v_max3_f32 v63, v63, v112, v113
	v_max3_f32 v63, v63, v114, v115
	v_pk_mul_f32 v[116:117], v[116:117], s[86:87] op_sel_hi:[1,0]
	v_pk_mul_f32 v[118:119], v[118:119], s[86:87] op_sel_hi:[1,0]
	v_max3_f32 v63, v63, v116, v117
	v_max3_f32 v63, v63, v118, v119
	s_nop 7
	v_pk_mul_f32 v[120:121], v[120:121], s[86:87] op_sel_hi:[1,0]
	v_pk_mul_f32 v[122:123], v[122:123], s[86:87] op_sel_hi:[1,0]
	v_max3_f32 v63, v63, v120, v121
	v_max3_f32 v63, v63, v122, v123
	v_pk_mul_f32 v[124:125], v[124:125], s[86:87] op_sel_hi:[1,0]
	v_pk_mul_f32 v[126:127], v[126:127], s[86:87] op_sel_hi:[1,0]
	v_max3_f32 v63, v63, v124, v125
	v_max3_f32 v63, v63, v126, v127
	ds_bpermute_b32 v8, v6, v63
	s_waitcnt lgkmcnt(0)
	v_max_f32_e32 v8, v8, v8
	v_max_f32_e32 v63, v63, v8
	ds_bpermute_b32 v8, v7, v63
	s_waitcnt lgkmcnt(0)
	v_max_f32_e32 v8, v8, v8
	v_max_f32_e32 v63, v63, v8
	v_mov_b32_e32 v62, 0
	v_sub_f32_e32 v64, v64, v63
	v_mul_f32_e32 v64, 0x3fb8aa3b, v64
	v_exp_f32_e32 v64, v64
	v_sub_f32_e32 v65, v65, v63
	v_mul_f32_e32 v65, 0x3fb8aa3b, v65
	v_exp_f32_e32 v65, v65
	v_add_f32_e32 v62, v64, v62
	v_sub_f32_e32 v66, v66, v63
	v_mul_f32_e32 v66, 0x3fb8aa3b, v66
	v_exp_f32_e32 v66, v66
	v_add_f32_e32 v62, v65, v62
	v_sub_f32_e32 v67, v67, v63
	v_mul_f32_e32 v67, 0x3fb8aa3b, v67
	v_exp_f32_e32 v67, v67
	v_add_f32_e32 v62, v66, v62
	v_sub_f32_e32 v68, v68, v63
	v_mul_f32_e32 v68, 0x3fb8aa3b, v68
	v_exp_f32_e32 v68, v68
	v_add_f32_e32 v62, v67, v62
	v_sub_f32_e32 v69, v69, v63
	v_mul_f32_e32 v69, 0x3fb8aa3b, v69
	v_exp_f32_e32 v69, v69
	v_add_f32_e32 v62, v68, v62
	v_sub_f32_e32 v70, v70, v63
	v_mul_f32_e32 v70, 0x3fb8aa3b, v70
	v_exp_f32_e32 v70, v70
	v_add_f32_e32 v62, v69, v62
	v_sub_f32_e32 v71, v71, v63
	v_mul_f32_e32 v71, 0x3fb8aa3b, v71
	v_exp_f32_e32 v71, v71
	v_add_f32_e32 v62, v70, v62
	v_sub_f32_e32 v72, v72, v63
	v_mul_f32_e32 v72, 0x3fb8aa3b, v72
	v_exp_f32_e32 v72, v72
	v_add_f32_e32 v62, v71, v62
	v_sub_f32_e32 v73, v73, v63
	v_mul_f32_e32 v73, 0x3fb8aa3b, v73
	v_exp_f32_e32 v73, v73
	v_add_f32_e32 v62, v72, v62
	v_sub_f32_e32 v74, v74, v63
	v_mul_f32_e32 v74, 0x3fb8aa3b, v74
	v_exp_f32_e32 v74, v74
	v_add_f32_e32 v62, v73, v62
	v_sub_f32_e32 v75, v75, v63
	v_mul_f32_e32 v75, 0x3fb8aa3b, v75
	v_exp_f32_e32 v75, v75
	v_add_f32_e32 v62, v74, v62
	v_sub_f32_e32 v76, v76, v63
	v_mul_f32_e32 v76, 0x3fb8aa3b, v76
	v_exp_f32_e32 v76, v76
	v_add_f32_e32 v62, v75, v62
	v_sub_f32_e32 v77, v77, v63
	v_mul_f32_e32 v77, 0x3fb8aa3b, v77
	v_exp_f32_e32 v77, v77
	v_add_f32_e32 v62, v76, v62
	v_sub_f32_e32 v78, v78, v63
	v_mul_f32_e32 v78, 0x3fb8aa3b, v78
	v_exp_f32_e32 v78, v78
	v_add_f32_e32 v62, v77, v62
	v_sub_f32_e32 v79, v79, v63
	v_mul_f32_e32 v79, 0x3fb8aa3b, v79
	v_exp_f32_e32 v79, v79
	v_add_f32_e32 v62, v78, v62
	v_sub_f32_e32 v80, v80, v63
	v_mul_f32_e32 v80, 0x3fb8aa3b, v80
	v_exp_f32_e32 v80, v80
	v_add_f32_e32 v62, v79, v62
	v_sub_f32_e32 v81, v81, v63
	v_mul_f32_e32 v81, 0x3fb8aa3b, v81
	v_exp_f32_e32 v81, v81
	v_add_f32_e32 v62, v80, v62
	v_sub_f32_e32 v82, v82, v63
	v_mul_f32_e32 v82, 0x3fb8aa3b, v82
	v_exp_f32_e32 v82, v82
	v_add_f32_e32 v62, v81, v62
	v_sub_f32_e32 v83, v83, v63
	v_mul_f32_e32 v83, 0x3fb8aa3b, v83
	v_exp_f32_e32 v83, v83
	v_add_f32_e32 v62, v82, v62
	v_sub_f32_e32 v84, v84, v63
	v_mul_f32_e32 v84, 0x3fb8aa3b, v84
	v_exp_f32_e32 v84, v84
	v_add_f32_e32 v62, v83, v62
	v_sub_f32_e32 v85, v85, v63
	v_mul_f32_e32 v85, 0x3fb8aa3b, v85
	v_exp_f32_e32 v85, v85
	v_add_f32_e32 v62, v84, v62
	v_sub_f32_e32 v86, v86, v63
	v_mul_f32_e32 v86, 0x3fb8aa3b, v86
; __device__ __forceinline__ void xattn_prompt_item(const bf16_t* xq, const bf16_t* xq1, const bf16_t* memkv, const bf16_t* memvt, bf16_t* xo, int l, int it, int lane) {
;     ...
;     mx = fmaxf(mx, __shfl_xor(mx, 16)); mx = fmaxf(mx, __shfl_xor(mx, 32));
;     float sum = 0.f;
; #pragma unroll
;     for (int kt = 0; kt < 16; ++kt)
; #pragma unroll
;         for (int j = 0; j < 4; ++j) { const float p = __expf(sc[kt][j] - mx); sc[kt][j] = p; sum += p; }
;     sum += __shfl_xor(sum, 16); sum += __shfl_xor(sum, 32);
;     const float inv = 1.0f / sum;
	v_exp_f32_e32 v86, v86
	v_add_f32_e32 v62, v85, v62
	v_sub_f32_e32 v87, v87, v63
	v_mul_f32_e32 v87, 0x3fb8aa3b, v87
	v_exp_f32_e32 v87, v87
	v_add_f32_e32 v62, v86, v62
	v_sub_f32_e32 v88, v88, v63
	v_mul_f32_e32 v88, 0x3fb8aa3b, v88
	v_exp_f32_e32 v88, v88
	v_add_f32_e32 v62, v87, v62
	v_sub_f32_e32 v89, v89, v63
	v_mul_f32_e32 v89, 0x3fb8aa3b, v89
	v_exp_f32_e32 v89, v89
	v_add_f32_e32 v62, v88, v62
	v_sub_f32_e32 v90, v90, v63
	v_mul_f32_e32 v90, 0x3fb8aa3b, v90
	v_exp_f32_e32 v90, v90
	v_add_f32_e32 v62, v89, v62
	v_sub_f32_e32 v91, v91, v63
	v_mul_f32_e32 v91, 0x3fb8aa3b, v91
	v_exp_f32_e32 v91, v91
	v_add_f32_e32 v62, v90, v62
	v_sub_f32_e32 v92, v92, v63
	v_mul_f32_e32 v92, 0x3fb8aa3b, v92
	v_exp_f32_e32 v92, v92
	v_add_f32_e32 v62, v91, v62
	v_sub_f32_e32 v93, v93, v63
	v_mul_f32_e32 v93, 0x3fb8aa3b, v93
	v_exp_f32_e32 v93, v93
	v_add_f32_e32 v62, v92, v62
	v_sub_f32_e32 v94, v94, v63
	v_mul_f32_e32 v94, 0x3fb8aa3b, v94
	v_exp_f32_e32 v94, v94
	v_add_f32_e32 v62, v93, v62
	v_sub_f32_e32 v95, v95, v63
	v_mul_f32_e32 v95, 0x3fb8aa3b, v95
	v_exp_f32_e32 v95, v95
	v_add_f32_e32 v62, v94, v62
	v_sub_f32_e32 v96, v96, v63
	v_mul_f32_e32 v96, 0x3fb8aa3b, v96
	v_exp_f32_e32 v96, v96
	v_add_f32_e32 v62, v95, v62
	v_sub_f32_e32 v97, v97, v63
	v_mul_f32_e32 v97, 0x3fb8aa3b, v97
	v_exp_f32_e32 v97, v97
	v_add_f32_e32 v62, v96, v62
	v_sub_f32_e32 v98, v98, v63
	v_mul_f32_e32 v98, 0x3fb8aa3b, v98
	v_exp_f32_e32 v98, v98
	v_add_f32_e32 v62, v97, v62
	v_sub_f32_e32 v99, v99, v63
	v_mul_f32_e32 v99, 0x3fb8aa3b, v99
	v_exp_f32_e32 v99, v99
	v_add_f32_e32 v62, v98, v62
	v_sub_f32_e32 v100, v100, v63
	v_mul_f32_e32 v100, 0x3fb8aa3b, v100
	v_exp_f32_e32 v100, v100
	v_add_f32_e32 v62, v99, v62
	v_sub_f32_e32 v101, v101, v63
	v_mul_f32_e32 v101, 0x3fb8aa3b, v101
	v_exp_f32_e32 v101, v101
	v_add_f32_e32 v62, v100, v62
	v_sub_f32_e32 v102, v102, v63
	v_mul_f32_e32 v102, 0x3fb8aa3b, v102
	v_exp_f32_e32 v102, v102
	v_add_f32_e32 v62, v101, v62
	v_sub_f32_e32 v103, v103, v63
	v_mul_f32_e32 v103, 0x3fb8aa3b, v103
	v_exp_f32_e32 v103, v103
	v_add_f32_e32 v62, v102, v62
	v_sub_f32_e32 v104, v104, v63
	v_mul_f32_e32 v104, 0x3fb8aa3b, v104
	v_exp_f32_e32 v104, v104
	v_add_f32_e32 v62, v103, v62
	v_sub_f32_e32 v105, v105, v63
	v_mul_f32_e32 v105, 0x3fb8aa3b, v105
	v_exp_f32_e32 v105, v105
	v_add_f32_e32 v62, v104, v62
	v_sub_f32_e32 v106, v106, v63
	v_mul_f32_e32 v106, 0x3fb8aa3b, v106
	v_exp_f32_e32 v106, v106
	v_add_f32_e32 v62, v105, v62
	v_sub_f32_e32 v107, v107, v63
	v_mul_f32_e32 v107, 0x3fb8aa3b, v107
	v_exp_f32_e32 v107, v107
	v_add_f32_e32 v62, v106, v62
	v_sub_f32_e32 v108, v108, v63
	v_mul_f32_e32 v108, 0x3fb8aa3b, v108
	v_exp_f32_e32 v108, v108
	v_add_f32_e32 v62, v107, v62
	v_sub_f32_e32 v109, v109, v63
	v_mul_f32_e32 v109, 0x3fb8aa3b, v109
	v_exp_f32_e32 v109, v109
	v_add_f32_e32 v62, v108, v62
	v_sub_f32_e32 v110, v110, v63
	v_mul_f32_e32 v110, 0x3fb8aa3b, v110
	v_exp_f32_e32 v110, v110
	v_add_f32_e32 v62, v109, v62
	v_sub_f32_e32 v111, v111, v63
	v_mul_f32_e32 v111, 0x3fb8aa3b, v111
	v_exp_f32_e32 v111, v111
	v_add_f32_e32 v62, v110, v62
	v_sub_f32_e32 v112, v112, v63
	v_mul_f32_e32 v112, 0x3fb8aa3b, v112
	v_exp_f32_e32 v112, v112
	v_add_f32_e32 v62, v111, v62
	v_sub_f32_e32 v113, v113, v63
	v_mul_f32_e32 v113, 0x3fb8aa3b, v113
	v_exp_f32_e32 v113, v113
	v_add_f32_e32 v62, v112, v62
	v_sub_f32_e32 v114, v114, v63
	v_mul_f32_e32 v114, 0x3fb8aa3b, v114
	v_exp_f32_e32 v114, v114
	v_add_f32_e32 v62, v113, v62
	v_sub_f32_e32 v115, v115, v63
	v_mul_f32_e32 v115, 0x3fb8aa3b, v115
	v_exp_f32_e32 v115, v115
	v_add_f32_e32 v62, v114, v62
	v_sub_f32_e32 v116, v116, v63
	v_mul_f32_e32 v116, 0x3fb8aa3b, v116
	v_exp_f32_e32 v116, v116
	v_add_f32_e32 v62, v115, v62
	v_sub_f32_e32 v117, v117, v63
	v_mul_f32_e32 v117, 0x3fb8aa3b, v117
	v_exp_f32_e32 v117, v117
	v_add_f32_e32 v62, v116, v62
	v_sub_f32_e32 v118, v118, v63
	v_mul_f32_e32 v118, 0x3fb8aa3b, v118
	v_exp_f32_e32 v118, v118
	v_add_f32_e32 v62, v117, v62
	v_sub_f32_e32 v119, v119, v63
	v_mul_f32_e32 v119, 0x3fb8aa3b, v119
	v_exp_f32_e32 v119, v119
	v_add_f32_e32 v62, v118, v62
	v_sub_f32_e32 v120, v120, v63
	v_mul_f32_e32 v120, 0x3fb8aa3b, v120
	v_exp_f32_e32 v120, v120
	v_add_f32_e32 v62, v119, v62
	v_sub_f32_e32 v121, v121, v63
	v_mul_f32_e32 v121, 0x3fb8aa3b, v121
	v_exp_f32_e32 v121, v121
	v_add_f32_e32 v62, v120, v62
	v_sub_f32_e32 v122, v122, v63
	v_mul_f32_e32 v122, 0x3fb8aa3b, v122
	v_exp_f32_e32 v122, v122
	v_add_f32_e32 v62, v121, v62
	v_sub_f32_e32 v123, v123, v63
	v_mul_f32_e32 v123, 0x3fb8aa3b, v123
	v_exp_f32_e32 v123, v123
	v_add_f32_e32 v62, v122, v62
	v_sub_f32_e32 v124, v124, v63
	v_mul_f32_e32 v124, 0x3fb8aa3b, v124
	v_exp_f32_e32 v124, v124
	v_add_f32_e32 v62, v123, v62
	v_sub_f32_e32 v125, v125, v63
	v_mul_f32_e32 v125, 0x3fb8aa3b, v125
	v_exp_f32_e32 v125, v125
	v_add_f32_e32 v62, v124, v62
	v_sub_f32_e32 v126, v126, v63
	v_mul_f32_e32 v126, 0x3fb8aa3b, v126
	v_exp_f32_e32 v126, v126
	v_add_f32_e32 v62, v125, v62
	v_sub_f32_e32 v127, v127, v63
	v_mul_f32_e32 v127, 0x3fb8aa3b, v127
	v_exp_f32_e32 v127, v127
	v_add_f32_e32 v62, v126, v62
	s_nop 0
	v_add_f32_e32 v62, v127, v62
	ds_bpermute_b32 v8, v6, v62
	s_waitcnt lgkmcnt(0)
	v_add_f32_e32 v62, v62, v8
	ds_bpermute_b32 v8, v7, v62
	s_waitcnt lgkmcnt(0)
; #define MFMA16(a, b, c) __builtin_amdgcn_mfma_f32_16x16x32_bf16((a), (b), (c), 0, 0, 0)
; __device__ __forceinline__ unsigned pk2(float lo, float hi) { return pg8::cvt_pk_bf16(lo, hi); }
; __device__ __forceinline__ void xattn_prompt_item(const bf16_t* xq, const bf16_t* xq1, const bf16_t* memkv, const bf16_t* memvt, bf16_t* xo, int l, int it, int lane) {
;     ...
;     sum += __shfl_xor(sum, 16); sum += __shfl_xor(sum, 32);
;     const float inv = 1.0f / sum;
;     f32x4 o[8];
; #pragma unroll
;     for (int mi = 0; mi < 8; ++mi) o[mi] = (f32x4){0.f, 0.f, 0.f, 0.f};
; #pragma unroll
;     for (int u = 0; u < 8; ++u) {
;         u32x4 pw; pw.x = pk2(sc[2 * u][0] * inv, sc[2 * u][1] * inv); pw.y = pk2(sc[2 * u][2] * inv, sc[2 * u][3] * inv);
;         pw.z = pk2(sc[2 * u + 1][0] * inv, sc[2 * u + 1][1] * inv); pw.w = pk2(sc[2 * u + 1][2] * inv, sc[2 * u + 1][3] * inv);
;         const bf16x8 pb = as_bf16x8(pw);
;         const int pos0 = 32 * u + 4 * g;
; #pragma unroll
;         for (int mi = 0; mi < 8; ++mi) {
;             const bf16_t* vp = memvt + ((size_t)((l * 2 + b) * 512 + h * 128 + 16 * mi + l15)) * 256 + pos0;
;             const s16x4 v0 = *(const s16x4*)vp, v1 = *(const s16x4*)(vp + 16);
;             const bf16x8 va = (bf16x8){v0[0], v0[1], v0[2], v0[3], v1[0], v1[1], v1[2], v1[3]};
;             o[mi] = MFMA16(va, pb, o[mi]);
;         }
	v_add_f32_e32 v0, v62, v8
	v_div_scale_f32 v8, s[18:19], v0, v0, 1.0
	v_rcp_f32_e32 v9, v8
	s_nop 0
	v_fma_f32 v136, -v8, v9, 1.0
	v_fmac_f32_e32 v9, v136, v9
	v_div_scale_f32 v136, vcc, 1.0, v0, 1.0
	v_mul_f32_e32 v137, v136, v9
	v_fma_f32 v62, -v8, v137, v136
	v_fmac_f32_e32 v137, v62, v9
	v_fma_f32 v8, -v8, v137, v136
	v_div_fmas_f32 v8, v8, v9, v137
	v_div_fixup_f32 v62, v8, v0, 1.0
	v_pk_mul_f32 v[8:9], v[64:65], v[62:63] op_sel_hi:[1,0]
	v_cvt_pk_bf16_f32 v64, v8, v9
	v_pk_mul_f32 v[8:9], v[66:67], v[62:63] op_sel_hi:[1,0]
	v_cvt_pk_bf16_f32 v65, v8, v9
	v_pk_mul_f32 v[8:9], v[68:69], v[62:63] op_sel_hi:[1,0]
	v_cvt_pk_bf16_f32 v66, v8, v9
	v_pk_mul_f32 v[8:9], v[70:71], v[62:63] op_sel_hi:[1,0]
	v_cvt_pk_bf16_f32 v67, v8, v9
	v_pk_mul_f32 v[8:9], v[72:73], v[62:63] op_sel_hi:[1,0]
	v_cvt_pk_bf16_f32 v68, v8, v9
	v_pk_mul_f32 v[8:9], v[74:75], v[62:63] op_sel_hi:[1,0]
	v_cvt_pk_bf16_f32 v69, v8, v9
	v_pk_mul_f32 v[8:9], v[76:77], v[62:63] op_sel_hi:[1,0]
	v_cvt_pk_bf16_f32 v70, v8, v9
	v_pk_mul_f32 v[8:9], v[78:79], v[62:63] op_sel_hi:[1,0]
	v_cvt_pk_bf16_f32 v71, v8, v9
	v_pk_mul_f32 v[8:9], v[80:81], v[62:63] op_sel_hi:[1,0]
	v_cvt_pk_bf16_f32 v72, v8, v9
	v_pk_mul_f32 v[8:9], v[82:83], v[62:63] op_sel_hi:[1,0]
	v_cvt_pk_bf16_f32 v73, v8, v9
	v_pk_mul_f32 v[8:9], v[84:85], v[62:63] op_sel_hi:[1,0]
	v_cvt_pk_bf16_f32 v74, v8, v9
	v_pk_mul_f32 v[8:9], v[86:87], v[62:63] op_sel_hi:[1,0]
	v_cvt_pk_bf16_f32 v75, v8, v9
	v_pk_mul_f32 v[8:9], v[88:89], v[62:63] op_sel_hi:[1,0]
	v_cvt_pk_bf16_f32 v76, v8, v9
	v_pk_mul_f32 v[8:9], v[90:91], v[62:63] op_sel_hi:[1,0]
	v_cvt_pk_bf16_f32 v77, v8, v9
	v_pk_mul_f32 v[8:9], v[92:93], v[62:63] op_sel_hi:[1,0]
	v_cvt_pk_bf16_f32 v78, v8, v9
	v_pk_mul_f32 v[8:9], v[94:95], v[62:63] op_sel_hi:[1,0]
	v_cvt_pk_bf16_f32 v79, v8, v9
	v_pk_mul_f32 v[8:9], v[96:97], v[62:63] op_sel_hi:[1,0]
	v_cvt_pk_bf16_f32 v80, v8, v9
	v_pk_mul_f32 v[8:9], v[98:99], v[62:63] op_sel_hi:[1,0]
	v_cvt_pk_bf16_f32 v81, v8, v9
	v_pk_mul_f32 v[8:9], v[100:101], v[62:63] op_sel_hi:[1,0]
	v_cvt_pk_bf16_f32 v82, v8, v9
	v_pk_mul_f32 v[8:9], v[102:103], v[62:63] op_sel_hi:[1,0]
	v_cvt_pk_bf16_f32 v83, v8, v9
	v_pk_mul_f32 v[8:9], v[104:105], v[62:63] op_sel_hi:[1,0]
	v_cvt_pk_bf16_f32 v84, v8, v9
	v_pk_mul_f32 v[8:9], v[106:107], v[62:63] op_sel_hi:[1,0]
	v_cvt_pk_bf16_f32 v85, v8, v9
	v_pk_mul_f32 v[8:9], v[108:109], v[62:63] op_sel_hi:[1,0]
	v_cvt_pk_bf16_f32 v86, v8, v9
	v_pk_mul_f32 v[8:9], v[110:111], v[62:63] op_sel_hi:[1,0]
	v_cvt_pk_bf16_f32 v87, v8, v9
	v_pk_mul_f32 v[8:9], v[112:113], v[62:63] op_sel_hi:[1,0]
	v_cvt_pk_bf16_f32 v88, v8, v9
	v_pk_mul_f32 v[8:9], v[114:115], v[62:63] op_sel_hi:[1,0]
	v_cvt_pk_bf16_f32 v89, v8, v9
	v_pk_mul_f32 v[8:9], v[116:117], v[62:63] op_sel_hi:[1,0]
	v_cvt_pk_bf16_f32 v90, v8, v9
	v_pk_mul_f32 v[8:9], v[118:119], v[62:63] op_sel_hi:[1,0]
	v_cvt_pk_bf16_f32 v91, v8, v9
	v_pk_mul_f32 v[8:9], v[120:121], v[62:63] op_sel_hi:[1,0]
	v_cvt_pk_bf16_f32 v92, v8, v9
	v_pk_mul_f32 v[8:9], v[122:123], v[62:63] op_sel_hi:[1,0]
	v_cvt_pk_bf16_f32 v93, v8, v9
	v_pk_mul_f32 v[8:9], v[124:125], v[62:63] op_sel_hi:[1,0]
	v_cvt_pk_bf16_f32 v94, v8, v9
	v_pk_mul_f32 v[8:9], v[126:127], v[62:63] op_sel_hi:[1,0]
	v_cvt_pk_bf16_f32 v95, v8, v9
	s_nop 1
	ds_read_b128 v[178:181], v4 offset:64
	ds_read_b128 v[182:185], v4 offset:8512
	ds_read_b128 v[186:189], v4 offset:16960
	ds_read_b128 v[190:193], v4 offset:25408
	s_waitcnt lgkmcnt(4)
	v_mfma_f32_16x16x32_bf16 v[26:29], v[146:149], v[64:67], 0
	v_mfma_f32_16x16x32_bf16 v[30:33], v[150:153], v[64:67], 0
	ds_read_b128 v[194:197], v4 offset:33856
	v_mfma_f32_16x16x32_bf16 v[34:37], v[154:157], v[64:67], 0
	v_mfma_f32_16x16x32_bf16 v[38:41], v[158:161], v[64:67], 0
	ds_read_b128 v[198:201], v4 offset:42304
	v_mfma_f32_16x16x32_bf16 v[42:45], v[162:165], v[64:67], 0
	v_mfma_f32_16x16x32_bf16 v[46:49], v[166:169], v[64:67], 0
	ds_read_b128 v[202:205], v4 offset:50752
	v_mfma_f32_16x16x32_bf16 v[50:53], v[170:173], v[64:67], 0
	v_mfma_f32_16x16x32_bf16 v[54:57], v[174:177], v[64:67], 0
	ds_read_b128 v[206:209], v4 offset:59200
	ds_read_b128 v[146:149], v4 offset:128
	ds_read_b128 v[150:153], v4 offset:8576
	ds_read_b128 v[154:157], v4 offset:17024
	ds_read_b128 v[158:161], v4 offset:25472
	s_waitcnt lgkmcnt(4)
	v_mfma_f32_16x16x32_bf16 v[26:29], v[178:181], v[68:71], v[26:29]
	v_mfma_f32_16x16x32_bf16 v[30:33], v[182:185], v[68:71], v[30:33]
	ds_read_b128 v[162:165], v4 offset:33920
	v_mfma_f32_16x16x32_bf16 v[34:37], v[186:189], v[68:71], v[34:37]
	v_mfma_f32_16x16x32_bf16 v[38:41], v[190:193], v[68:71], v[38:41]
	ds_read_b128 v[166:169], v4 offset:42368
	v_mfma_f32_16x16x32_bf16 v[42:45], v[194:197], v[68:71], v[42:45]
	v_mfma_f32_16x16x32_bf16 v[46:49], v[198:201], v[68:71], v[46:49]
	ds_read_b128 v[170:173], v4 offset:50816
	v_mfma_f32_16x16x32_bf16 v[50:53], v[202:205], v[68:71], v[50:53]
	v_mfma_f32_16x16x32_bf16 v[54:57], v[206:209], v[68:71], v[54:57]
	ds_read_b128 v[174:177], v4 offset:59264
	ds_read_b128 v[178:181], v4 offset:192
	ds_read_b128 v[182:185], v4 offset:8640
	ds_read_b128 v[186:189], v4 offset:17088
	ds_read_b128 v[190:193], v4 offset:25536
	s_waitcnt lgkmcnt(4)
	v_mfma_f32_16x16x32_bf16 v[26:29], v[146:149], v[72:75], v[26:29]
	v_mfma_f32_16x16x32_bf16 v[30:33], v[150:153], v[72:75], v[30:33]
	ds_read_b128 v[194:197], v4 offset:33984
	v_mfma_f32_16x16x32_bf16 v[34:37], v[154:157], v[72:75], v[34:37]
	v_mfma_f32_16x16x32_bf16 v[38:41], v[158:161], v[72:75], v[38:41]
	ds_read_b128 v[198:201], v4 offset:42432
	v_mfma_f32_16x16x32_bf16 v[42:45], v[162:165], v[72:75], v[42:45]
	v_mfma_f32_16x16x32_bf16 v[46:49], v[166:169], v[72:75], v[46:49]
	ds_read_b128 v[202:205], v4 offset:50880
	v_mfma_f32_16x16x32_bf16 v[50:53], v[170:173], v[72:75], v[50:53]
	v_mfma_f32_16x16x32_bf16 v[54:57], v[174:177], v[72:75], v[54:57]
	ds_read_b128 v[206:209], v4 offset:59328
	ds_read_b128 v[146:149], v4 offset:256
	ds_read_b128 v[150:153], v4 offset:8704
	ds_read_b128 v[154:157], v4 offset:17152
	ds_read_b128 v[158:161], v4 offset:25600
	s_waitcnt lgkmcnt(4)
; #define MFMA16(a, b, c) __builtin_amdgcn_mfma_f32_16x16x32_bf16((a), (b), (c), 0, 0, 0)
; __device__ __forceinline__ unsigned pk2(float lo, float hi) { return pg8::cvt_pk_bf16(lo, hi); }
; __device__ __forceinline__ void xattn_prompt_item(const bf16_t* xq, const bf16_t* xq1, const bf16_t* memkv, const bf16_t* memvt, bf16_t* xo, int l, int it, int lane) {
;     ...
; #pragma unroll
;     for (int u = 0; u < 8; ++u) {
;         u32x4 pw; pw.x = pk2(sc[2 * u][0] * inv, sc[2 * u][1] * inv); pw.y = pk2(sc[2 * u][2] * inv, sc[2 * u][3] * inv);
;         pw.z = pk2(sc[2 * u + 1][0] * inv, sc[2 * u + 1][1] * inv); pw.w = pk2(sc[2 * u + 1][2] * inv, sc[2 * u + 1][3] * inv);
;         const bf16x8 pb = as_bf16x8(pw);
;         const int pos0 = 32 * u + 4 * g;
; #pragma unroll
;         for (int mi = 0; mi < 8; ++mi) {
;             const bf16_t* vp = memvt + ((size_t)((l * 2 + b) * 512 + h * 128 + 16 * mi + l15)) * 256 + pos0;
;             const s16x4 v0 = *(const s16x4*)vp, v1 = *(const s16x4*)(vp + 16);
;             const bf16x8 va = (bf16x8){v0[0], v0[1], v0[2], v0[3], v1[0], v1[1], v1[2], v1[3]};
;             o[mi] = MFMA16(va, pb, o[mi]);
;         }
;     }
; #pragma unroll
;     for (int mi = 0; mi < 8; ++mi) {
;         u32x2 w; w.x = pk2(o[mi][0], o[mi][1]); w.y = pk2(o[mi][2], o[mi][3]);
;         *(u32x2*)(xo + tok * 512 + h * 128 + 16 * mi + 4 * g) = w;
;     }
; __global__ void __launch_bounds__(NTHREADS, 2) hybrid_fwd(Params P) {
;     ...
;             if (PHS(18)) for (int it = gw; it < 2048; it += NGW) xattn_prompt_item(XQ, XQ1, MEMKV, MEMVT, XO, l, it, lane);
	v_mfma_f32_16x16x32_bf16 v[26:29], v[178:181], v[76:79], v[26:29]
	v_mfma_f32_16x16x32_bf16 v[30:33], v[182:185], v[76:79], v[30:33]
	ds_read_b128 v[162:165], v4 offset:34048
	v_mfma_f32_16x16x32_bf16 v[34:37], v[186:189], v[76:79], v[34:37]
	v_mfma_f32_16x16x32_bf16 v[38:41], v[190:193], v[76:79], v[38:41]
	ds_read_b128 v[166:169], v4 offset:42496
	v_mfma_f32_16x16x32_bf16 v[42:45], v[194:197], v[76:79], v[42:45]
	v_mfma_f32_16x16x32_bf16 v[46:49], v[198:201], v[76:79], v[46:49]
	ds_read_b128 v[170:173], v4 offset:50944
	v_mfma_f32_16x16x32_bf16 v[50:53], v[202:205], v[76:79], v[50:53]
	v_mfma_f32_16x16x32_bf16 v[54:57], v[206:209], v[76:79], v[54:57]
	ds_read_b128 v[174:177], v4 offset:59392
	ds_read_b128 v[178:181], v4 offset:320
	ds_read_b128 v[182:185], v4 offset:8768
	ds_read_b128 v[186:189], v4 offset:17216
	ds_read_b128 v[190:193], v4 offset:25664
	s_waitcnt lgkmcnt(4)
	v_mfma_f32_16x16x32_bf16 v[26:29], v[146:149], v[80:83], v[26:29]
	v_mfma_f32_16x16x32_bf16 v[30:33], v[150:153], v[80:83], v[30:33]
	ds_read_b128 v[194:197], v4 offset:34112
	v_mfma_f32_16x16x32_bf16 v[34:37], v[154:157], v[80:83], v[34:37]
	v_mfma_f32_16x16x32_bf16 v[38:41], v[158:161], v[80:83], v[38:41]
	ds_read_b128 v[198:201], v4 offset:42560
	v_mfma_f32_16x16x32_bf16 v[42:45], v[162:165], v[80:83], v[42:45]
	v_mfma_f32_16x16x32_bf16 v[46:49], v[166:169], v[80:83], v[46:49]
	ds_read_b128 v[202:205], v4 offset:51008
	v_mfma_f32_16x16x32_bf16 v[50:53], v[170:173], v[80:83], v[50:53]
	v_mfma_f32_16x16x32_bf16 v[54:57], v[174:177], v[80:83], v[54:57]
	ds_read_b128 v[206:209], v4 offset:59456
	ds_read_b128 v[146:149], v4 offset:384
	ds_read_b128 v[150:153], v4 offset:8832
	ds_read_b128 v[154:157], v4 offset:17280
	ds_read_b128 v[158:161], v4 offset:25728
	s_waitcnt lgkmcnt(4)
	v_mfma_f32_16x16x32_bf16 v[26:29], v[178:181], v[84:87], v[26:29]
	v_mfma_f32_16x16x32_bf16 v[30:33], v[182:185], v[84:87], v[30:33]
	ds_read_b128 v[162:165], v4 offset:34176
	v_mfma_f32_16x16x32_bf16 v[34:37], v[186:189], v[84:87], v[34:37]
	v_mfma_f32_16x16x32_bf16 v[38:41], v[190:193], v[84:87], v[38:41]
	ds_read_b128 v[166:169], v4 offset:42624
	v_mfma_f32_16x16x32_bf16 v[42:45], v[194:197], v[84:87], v[42:45]
	v_mfma_f32_16x16x32_bf16 v[46:49], v[198:201], v[84:87], v[46:49]
	ds_read_b128 v[170:173], v4 offset:51072
	v_mfma_f32_16x16x32_bf16 v[50:53], v[202:205], v[84:87], v[50:53]
	v_mfma_f32_16x16x32_bf16 v[54:57], v[206:209], v[84:87], v[54:57]
	ds_read_b128 v[174:177], v4 offset:59520
	ds_read_b128 v[178:181], v4 offset:448
	ds_read_b128 v[182:185], v4 offset:8896
	ds_read_b128 v[186:189], v4 offset:17344
	ds_read_b128 v[190:193], v4 offset:25792
	s_waitcnt lgkmcnt(4)
	v_mfma_f32_16x16x32_bf16 v[26:29], v[146:149], v[88:91], v[26:29]
	v_mfma_f32_16x16x32_bf16 v[30:33], v[150:153], v[88:91], v[30:33]
	ds_read_b128 v[194:197], v4 offset:34240
	v_mfma_f32_16x16x32_bf16 v[34:37], v[154:157], v[88:91], v[34:37]
	v_mfma_f32_16x16x32_bf16 v[38:41], v[158:161], v[88:91], v[38:41]
	ds_read_b128 v[198:201], v4 offset:42688
	v_mfma_f32_16x16x32_bf16 v[42:45], v[162:165], v[88:91], v[42:45]
	v_mfma_f32_16x16x32_bf16 v[46:49], v[166:169], v[88:91], v[46:49]
	ds_read_b128 v[202:205], v4 offset:51136
	v_mfma_f32_16x16x32_bf16 v[50:53], v[170:173], v[88:91], v[50:53]
	v_mfma_f32_16x16x32_bf16 v[54:57], v[174:177], v[88:91], v[54:57]
	ds_read_b128 v[206:209], v4 offset:59584
	s_waitcnt lgkmcnt(0)
	v_mfma_f32_16x16x32_bf16 v[26:29], v[178:181], v[92:95], v[26:29]
	v_mfma_f32_16x16x32_bf16 v[30:33], v[182:185], v[92:95], v[30:33]
	v_mfma_f32_16x16x32_bf16 v[34:37], v[186:189], v[92:95], v[34:37]
	v_mfma_f32_16x16x32_bf16 v[38:41], v[190:193], v[92:95], v[38:41]
	v_mfma_f32_16x16x32_bf16 v[42:45], v[194:197], v[92:95], v[42:45]
	v_mfma_f32_16x16x32_bf16 v[46:49], v[198:201], v[92:95], v[46:49]
	v_mfma_f32_16x16x32_bf16 v[50:53], v[202:205], v[92:95], v[50:53]
	v_mfma_f32_16x16x32_bf16 v[54:57], v[206:209], v[92:95], v[54:57]
	s_nop 7
	v_cvt_pk_bf16_f32 v8, v26, v27
	v_cvt_pk_bf16_f32 v9, v28, v29
	global_store_dwordx2 v5, v[8:9], s[4:5] offset:0
	s_nop 0
	v_cvt_pk_bf16_f32 v8, v30, v31
	v_cvt_pk_bf16_f32 v9, v32, v33
	global_store_dwordx2 v5, v[8:9], s[4:5] offset:32
	s_nop 0
	v_cvt_pk_bf16_f32 v8, v34, v35
	v_cvt_pk_bf16_f32 v9, v36, v37
	global_store_dwordx2 v5, v[8:9], s[4:5] offset:64
	s_nop 0
	v_cvt_pk_bf16_f32 v8, v38, v39
	v_cvt_pk_bf16_f32 v9, v40, v41
	global_store_dwordx2 v5, v[8:9], s[4:5] offset:96
	s_nop 0
	v_cvt_pk_bf16_f32 v8, v42, v43
	v_cvt_pk_bf16_f32 v9, v44, v45
	global_store_dwordx2 v5, v[8:9], s[4:5] offset:128
	s_nop 0
	v_cvt_pk_bf16_f32 v8, v46, v47
	v_cvt_pk_bf16_f32 v9, v48, v49
	global_store_dwordx2 v5, v[8:9], s[4:5] offset:160
	s_nop 0
	v_cvt_pk_bf16_f32 v8, v50, v51
	v_cvt_pk_bf16_f32 v9, v52, v53
	global_store_dwordx2 v5, v[8:9], s[4:5] offset:192
	s_nop 0
	v_cvt_pk_bf16_f32 v8, v54, v55
	v_cvt_pk_bf16_f32 v9, v56, v57
	global_store_dwordx2 v5, v[8:9], s[4:5] offset:224
	s_nop 0
	s_cmpk_eq_i32 s88, 0x100
	s_cbranch_scc0 .Lxp_next
	s_cmp_lg_u32 s28, 0
	s_cbranch_scc1 .LBB0_1405
	s_mov_b32 s28, 1
	s_add_i32 s6, s6, 4
	s_branch .Lxp_pair
.Lxp_next:
	s_cmpk_eq_i32 s88, 0x100
	s_cselect_b32 s7, 0x80, s88
	s_add_i32 s6, s6, s7
	s_cmpk_gt_i32 s6, 0xff
	s_cbranch_scc1 .LBB0_1405
	s_barrier
	s_branch .Lxp_pair
